# up-GEMM epilogue (rstd/shift, depthwise conv3 over tokens, silu gate, bf16 store) rewritten by hand: DPP row shifts folded into v_fmac, packed f32 for the gate math; same f32 math order
# speedup vs baseline: 1.0597x; 1.0244x over previous
.LBB0_883:
	s_lshl_b64 s[2:3], s[2:3], 2
	s_add_u32 s1, s58, s2
	s_addc_u32 s9, s59, s3
	s_lshl_b32 s2, s0, 8
	s_ashr_i32 s3, s2, 31
	s_lshl_b64 s[2:3], s[2:3], 2
	s_add_u32 s1, s1, s2
	s_addc_u32 s3, s9, s3
	s_add_u32 s2, s1, s66
	s_addc_u32 s3, s3, 0
	s_lshl_b32 s1, s8, 8
	s_add_i32 s1, s1, s60
	v_add_u32_e32 v192, s1, v239
	v_ashrrev_i32_e32 v193, 31, v192
	v_lshl_add_u64 v[104:105], v[192:193], 2, s[22:23]
	global_load_dword v193, v[104:105], off
	global_load_dword v196, v[104:105], off offset:64
	s_lshl_b32 s0, s0, 7
	v_lshlrev_b32_e32 v106, 3, v48
	s_or_b32 s0, s0, s61
	v_add_u32_e32 v190, s0, v106
	v_ashrrev_i32_e32 v107, 31, v106
	v_ashrrev_i32_e32 v191, 31, v190
	v_lshl_add_u64 v[48:49], v[106:107], 2, s[2:3]
	v_lshlrev_b64 v[106:107], 2, v[190:191]
	global_load_dwordx4 v[120:123], v[48:49], off
	global_load_dwordx4 v[116:119], v[48:49], off offset:512
	global_load_dwordx4 v[52:55], v[48:49], off offset:16
	s_nop 0
	global_load_dwordx4 v[48:51], v[48:49], off offset:528
	s_nop 0
	global_load_dword v243, v[104:105], off offset:128
	global_load_dword v242, v[104:105], off offset:192
	global_load_dword v241, v[104:105], off offset:512
	global_load_dword v240, v[104:105], off offset:576
	global_load_dword v199, v[104:105], off offset:640
	global_load_dword v197, v[104:105], off offset:704
	v_lshl_add_u64 v[194:195], s[20:21], 0, v[106:107]
	v_lshl_add_u64 v[104:105], s[24:25], 0, v[106:107]
	v_lshl_add_u64 v[108:109], s[26:27], 0, v[106:107]
	v_lshl_add_u64 v[110:111], s[28:29], 0, v[106:107]
	v_lshl_add_u64 v[160:161], s[30:31], 0, v[106:107]
	v_lshl_add_u64 v[200:201], s[34:35], 0, v[106:107]
	global_load_dwordx4 v[220:223], v[194:195], off offset:16
	global_load_dwordx4 v[156:159], v[194:195], off
	s_nop 0
	global_load_dwordx4 v[204:207], v[104:105], off offset:16
	global_load_dwordx4 v[104:107], v[104:105], off
	s_nop 0
	global_load_dwordx4 v[208:211], v[108:109], off offset:16
	global_load_dwordx4 v[164:167], v[108:109], off
	global_load_dwordx4 v[212:215], v[110:111], off offset:16
	global_load_dwordx4 v[112:115], v[110:111], off
	s_nop 0
	global_load_dwordx4 v[216:219], v[160:161], off offset:16
	global_load_dwordx4 v[160:163], v[160:161], off
	s_nop 0
	global_load_dwordx4 v[108:111], v[200:201], off
	global_load_dwordx4 v[200:203], v[200:201], off offset:16
	v_cmp_ne_u32_e64 s[10:11], 0, v239
	v_cmp_ne_u32_e64 s[8:9], 15, v239
	v_cmp_gt_u32_e64 s[12:13], 2, v239
	v_cmp_lt_u32_e64 s[14:15], 13, v239
	s_mov_b32 s0, 0xbfb8aa3b
	s_mov_b32 s1, 0xbfb8aa3b
	s_mov_b64 s[2:3], 0x16000
	s_waitcnt vmcnt(0)
	v_fmamk_f32 v244, v193, 0x3a800000, v225
	v_fmamk_f32 v196, v196, 0x3a800000, v225
	v_fmamk_f32 v246, v243, 0x3a800000, v225
	v_fmamk_f32 v242, v242, 0x3a800000, v225
	v_fmamk_f32 v248, v241, 0x3a800000, v225
	v_fmamk_f32 v240, v240, 0x3a800000, v225
	v_fmamk_f32 v198, v199, 0x3a800000, v225
	v_fmamk_f32 v250, v197, 0x3a800000, v225
	v_rsq_f32_e32 v244, v244
	v_rsq_f32_e32 v196, v196
	v_rsq_f32_e32 v246, v246
	v_rsq_f32_e32 v242, v242
	v_rsq_f32_e32 v248, v248
	v_rsq_f32_e32 v240, v240
	v_rsq_f32_e32 v198, v198
	v_rsq_f32_e32 v250, v250
	v_pk_fma_f32 v[152:153], v[152:153], v[244:245], v[120:121] op_sel_hi:[1,0,1]
	v_pk_fma_f32 v[154:155], v[154:155], v[244:245], v[122:123] op_sel_hi:[1,0,1]
	v_pk_fma_f32 v[68:69], v[68:69], v[244:245], v[52:53] op_sel_hi:[1,0,1]
	v_pk_fma_f32 v[70:71], v[70:71], v[244:245], v[54:55] op_sel_hi:[1,0,1]
	v_pk_fma_f32 v[144:145], v[144:145], v[244:245], v[116:117] op_sel_hi:[1,0,1]
	v_pk_fma_f32 v[146:147], v[146:147], v[244:245], v[118:119] op_sel_hi:[1,0,1]
	v_pk_fma_f32 v[60:61], v[60:61], v[244:245], v[48:49] op_sel_hi:[1,0,1]
	v_pk_fma_f32 v[62:63], v[62:63], v[244:245], v[50:51] op_sel_hi:[1,0,1]
	v_pk_fma_f32 v[148:149], v[148:149], v[196:197], v[120:121] op_sel_hi:[1,0,1]
	v_pk_fma_f32 v[150:151], v[150:151], v[196:197], v[122:123] op_sel_hi:[1,0,1]
	v_pk_fma_f32 v[64:65], v[64:65], v[196:197], v[52:53] op_sel_hi:[1,0,1]
	v_pk_fma_f32 v[66:67], v[66:67], v[196:197], v[54:55] op_sel_hi:[1,0,1]
	v_pk_fma_f32 v[140:141], v[140:141], v[196:197], v[116:117] op_sel_hi:[1,0,1]
	v_pk_fma_f32 v[142:143], v[142:143], v[196:197], v[118:119] op_sel_hi:[1,0,1]
	v_pk_fma_f32 v[56:57], v[56:57], v[196:197], v[48:49] op_sel_hi:[1,0,1]
	v_pk_fma_f32 v[58:59], v[58:59], v[196:197], v[50:51] op_sel_hi:[1,0,1]
	v_pk_fma_f32 v[136:137], v[136:137], v[246:247], v[120:121] op_sel_hi:[1,0,1]
	v_pk_fma_f32 v[138:139], v[138:139], v[246:247], v[122:123] op_sel_hi:[1,0,1]
	v_pk_fma_f32 v[44:45], v[44:45], v[246:247], v[52:53] op_sel_hi:[1,0,1]
	v_pk_fma_f32 v[46:47], v[46:47], v[246:247], v[54:55] op_sel_hi:[1,0,1]
	v_pk_fma_f32 v[132:133], v[132:133], v[246:247], v[116:117] op_sel_hi:[1,0,1]
	v_pk_fma_f32 v[134:135], v[134:135], v[246:247], v[118:119] op_sel_hi:[1,0,1]
	v_pk_fma_f32 v[36:37], v[36:37], v[246:247], v[48:49] op_sel_hi:[1,0,1]
	v_pk_fma_f32 v[38:39], v[38:39], v[246:247], v[50:51] op_sel_hi:[1,0,1]
	v_pk_fma_f32 v[128:129], v[128:129], v[242:243], v[120:121] op_sel_hi:[1,0,1]
	v_pk_fma_f32 v[130:131], v[130:131], v[242:243], v[122:123] op_sel_hi:[1,0,1]
	v_pk_fma_f32 v[40:41], v[40:41], v[242:243], v[52:53] op_sel_hi:[1,0,1]
	v_pk_fma_f32 v[42:43], v[42:43], v[242:243], v[54:55] op_sel_hi:[1,0,1]
	v_pk_fma_f32 v[124:125], v[124:125], v[242:243], v[116:117] op_sel_hi:[1,0,1]
	v_pk_fma_f32 v[126:127], v[126:127], v[242:243], v[118:119] op_sel_hi:[1,0,1]
	v_pk_fma_f32 v[32:33], v[32:33], v[242:243], v[48:49] op_sel_hi:[1,0,1]
	v_pk_fma_f32 v[34:35], v[34:35], v[242:243], v[50:51] op_sel_hi:[1,0,1]
	v_pk_fma_f32 v[100:101], v[100:101], v[248:249], v[120:121] op_sel_hi:[1,0,1]
	v_pk_fma_f32 v[102:103], v[102:103], v[248:249], v[122:123] op_sel_hi:[1,0,1]
	v_pk_fma_f32 v[28:29], v[28:29], v[248:249], v[52:53] op_sel_hi:[1,0,1]
	v_pk_fma_f32 v[30:31], v[30:31], v[248:249], v[54:55] op_sel_hi:[1,0,1]
	v_pk_fma_f32 v[92:93], v[92:93], v[248:249], v[116:117] op_sel_hi:[1,0,1]
	v_pk_fma_f32 v[94:95], v[94:95], v[248:249], v[118:119] op_sel_hi:[1,0,1]
	v_pk_fma_f32 v[20:21], v[20:21], v[248:249], v[48:49] op_sel_hi:[1,0,1]
	v_pk_fma_f32 v[22:23], v[22:23], v[248:249], v[50:51] op_sel_hi:[1,0,1]
	v_pk_fma_f32 v[96:97], v[96:97], v[240:241], v[120:121] op_sel_hi:[1,0,1]
	v_pk_fma_f32 v[98:99], v[98:99], v[240:241], v[122:123] op_sel_hi:[1,0,1]
	v_pk_fma_f32 v[24:25], v[24:25], v[240:241], v[52:53] op_sel_hi:[1,0,1]
	v_pk_fma_f32 v[26:27], v[26:27], v[240:241], v[54:55] op_sel_hi:[1,0,1]
	v_pk_fma_f32 v[88:89], v[88:89], v[240:241], v[116:117] op_sel_hi:[1,0,1]
	v_pk_fma_f32 v[90:91], v[90:91], v[240:241], v[118:119] op_sel_hi:[1,0,1]
	v_pk_fma_f32 v[16:17], v[16:17], v[240:241], v[48:49] op_sel_hi:[1,0,1]
	v_pk_fma_f32 v[18:19], v[18:19], v[240:241], v[50:51] op_sel_hi:[1,0,1]
	v_pk_fma_f32 v[84:85], v[84:85], v[198:199], v[120:121] op_sel_hi:[1,0,1]
	v_pk_fma_f32 v[86:87], v[86:87], v[198:199], v[122:123] op_sel_hi:[1,0,1]
	v_pk_fma_f32 v[12:13], v[12:13], v[198:199], v[52:53] op_sel_hi:[1,0,1]
	v_pk_fma_f32 v[14:15], v[14:15], v[198:199], v[54:55] op_sel_hi:[1,0,1]
	v_pk_fma_f32 v[80:81], v[80:81], v[198:199], v[116:117] op_sel_hi:[1,0,1]
	v_pk_fma_f32 v[82:83], v[82:83], v[198:199], v[118:119] op_sel_hi:[1,0,1]
	v_pk_fma_f32 v[4:5], v[4:5], v[198:199], v[48:49] op_sel_hi:[1,0,1]
	v_pk_fma_f32 v[6:7], v[6:7], v[198:199], v[50:51] op_sel_hi:[1,0,1]
	v_pk_fma_f32 v[76:77], v[76:77], v[250:251], v[120:121] op_sel_hi:[1,0,1]
	v_pk_fma_f32 v[78:79], v[78:79], v[250:251], v[122:123] op_sel_hi:[1,0,1]
	v_pk_fma_f32 v[8:9], v[8:9], v[250:251], v[52:53] op_sel_hi:[1,0,1]
	v_pk_fma_f32 v[10:11], v[10:11], v[250:251], v[54:55] op_sel_hi:[1,0,1]
	v_pk_fma_f32 v[72:73], v[72:73], v[250:251], v[116:117] op_sel_hi:[1,0,1]
	v_pk_fma_f32 v[74:75], v[74:75], v[250:251], v[118:119] op_sel_hi:[1,0,1]
	v_pk_fma_f32 v[0:1], v[0:1], v[250:251], v[48:49] op_sel_hi:[1,0,1]
	v_pk_fma_f32 v[2:3], v[2:3], v[250:251], v[50:51] op_sel_hi:[1,0,1]
	v_mov_b64_e32 v[246:247], s[16:17]
	v_mad_i64_i32 v[246:247], vcc, v192, s90, v[246:247]
	v_lshl_add_u64 v[246:247], v[190:191], 1, v[246:247]
	v_ashrrev_i32_e32 v194, 4, v192
	v_and_b32_e32 v194, -4, v194
	v_add_u32_e32 v194, v194, v239
	v_mov_b64_e32 v[248:249], s[18:19]
	v_mad_i64_i32 v[248:249], vcc, v194, s91, v[248:249]
	v_lshl_add_u64 v[248:249], v[190:191], 1, v[248:249]
	v_mov_b32_e32 v244, v246
	v_mov_b32_e32 v245, v247
	v_mov_b32_e32 v250, v248
	v_mov_b32_e32 v251, v249
	v_add_co_u32_e32 v194, vcc, 0x1000, v250
	s_nop 1
	v_addc_co_u32_e32 v195, vcc, 0, v251, vcc
	v_mul_f32_e32 v116, v164, v152
	v_mul_f32_e32 v117, v165, v153
	v_mul_f32_e32 v118, v166, v154
	v_mul_f32_e32 v119, v167, v155
	v_mul_f32_e32 v120, v112, v144
	v_mul_f32_e32 v121, v113, v145
	v_mul_f32_e32 v122, v114, v146
	v_mul_f32_e32 v123, v115, v147
	v_fmac_f32_dpp v116, v152, v156 row_shr:1 row_mask:0xf bank_mask:0xf bound_ctrl:1
	v_fmac_f32_dpp v117, v153, v157 row_shr:1 row_mask:0xf bank_mask:0xf bound_ctrl:1
	v_fmac_f32_dpp v118, v154, v158 row_shr:1 row_mask:0xf bank_mask:0xf bound_ctrl:1
	v_fmac_f32_dpp v119, v155, v159 row_shr:1 row_mask:0xf bank_mask:0xf bound_ctrl:1
	v_fmac_f32_dpp v120, v144, v104 row_shr:1 row_mask:0xf bank_mask:0xf bound_ctrl:1
	v_fmac_f32_dpp v121, v145, v105 row_shr:1 row_mask:0xf bank_mask:0xf bound_ctrl:1
	v_fmac_f32_dpp v122, v146, v106 row_shr:1 row_mask:0xf bank_mask:0xf bound_ctrl:1
	v_fmac_f32_dpp v123, v147, v107 row_shr:1 row_mask:0xf bank_mask:0xf bound_ctrl:1
	v_fmac_f32_dpp v116, v152, v160 row_shl:1 row_mask:0xf bank_mask:0xf bound_ctrl:1
	v_fmac_f32_dpp v117, v153, v161 row_shl:1 row_mask:0xf bank_mask:0xf bound_ctrl:1
	v_fmac_f32_dpp v118, v154, v162 row_shl:1 row_mask:0xf bank_mask:0xf bound_ctrl:1
	v_fmac_f32_dpp v119, v155, v163 row_shl:1 row_mask:0xf bank_mask:0xf bound_ctrl:1
	v_fmac_f32_dpp v120, v144, v108 row_shl:1 row_mask:0xf bank_mask:0xf bound_ctrl:1
	v_fmac_f32_dpp v121, v145, v109 row_shl:1 row_mask:0xf bank_mask:0xf bound_ctrl:1
	v_fmac_f32_dpp v122, v146, v110 row_shl:1 row_mask:0xf bank_mask:0xf bound_ctrl:1
	v_fmac_f32_dpp v123, v147, v111 row_shl:1 row_mask:0xf bank_mask:0xf bound_ctrl:1
	v_fmac_f32_dpp v116, v148, v160 row_shr:15 row_mask:0xf bank_mask:0xf bound_ctrl:1
	v_fmac_f32_dpp v117, v149, v161 row_shr:15 row_mask:0xf bank_mask:0xf bound_ctrl:1
	v_fmac_f32_dpp v118, v150, v162 row_shr:15 row_mask:0xf bank_mask:0xf bound_ctrl:1
	v_fmac_f32_dpp v119, v151, v163 row_shr:15 row_mask:0xf bank_mask:0xf bound_ctrl:1
	v_fmac_f32_dpp v120, v140, v108 row_shr:15 row_mask:0xf bank_mask:0xf bound_ctrl:1
	v_fmac_f32_dpp v121, v141, v109 row_shr:15 row_mask:0xf bank_mask:0xf bound_ctrl:1
	v_fmac_f32_dpp v122, v142, v110 row_shr:15 row_mask:0xf bank_mask:0xf bound_ctrl:1
	v_fmac_f32_dpp v123, v143, v111 row_shr:15 row_mask:0xf bank_mask:0xf bound_ctrl:1
	v_pk_mul_f32 v[48:49], v[116:117], s[0:1]
	v_pk_mul_f32 v[50:51], v[118:119], s[0:1]
	v_pk_mul_f32 v[52:53], v[116:117], v[120:121]
	v_pk_mul_f32 v[54:55], v[118:119], v[122:123]
	v_exp_f32_e32 v48, v48
	v_exp_f32_e32 v49, v49
	v_exp_f32_e32 v50, v50
	v_exp_f32_e32 v51, v51
	v_cvt_pk_bf16_f32 v196, v152, v153
	v_cvt_pk_bf16_f32 v197, v154, v155
	v_cvt_pk_bf16_f32 v198, v144, v145
	v_cvt_pk_bf16_f32 v199, v146, v147
	v_pk_add_f32 v[48:49], v[48:49], 1.0 op_sel_hi:[1,0]
	v_pk_add_f32 v[50:51], v[50:51], 1.0 op_sel_hi:[1,0]
	v_rcp_f32_e32 v48, v48
	v_rcp_f32_e32 v49, v49
	v_rcp_f32_e32 v50, v50
	v_rcp_f32_e32 v51, v51
	s_nop 0
	v_pk_mul_f32 v[52:53], v[52:53], v[48:49]
	v_pk_mul_f32 v[54:55], v[54:55], v[50:51]
	v_cvt_pk_bf16_f32 v252, v52, v53
	v_cvt_pk_bf16_f32 v253, v54, v55
	s_and_saveexec_b64 vcc, s[10:11]
	global_store_dwordx2 v[244:245], v[252:253], off
	s_mov_b64 exec, vcc
	s_and_saveexec_b64 vcc, s[12:13]
	global_store_dwordx2 v[250:251], v[196:197], off
	global_store_dwordx2 v[194:195], v[198:199], off offset:1536
	s_mov_b64 exec, vcc
	v_lshl_add_u64 v[244:245], v[244:245], 0, s[2:3]
	v_mul_f32_e32 v116, v164, v148
	v_mul_f32_e32 v117, v165, v149
	v_mul_f32_e32 v118, v166, v150
	v_mul_f32_e32 v119, v167, v151
	v_mul_f32_e32 v120, v112, v140
	v_mul_f32_e32 v121, v113, v141
	v_mul_f32_e32 v122, v114, v142
	v_mul_f32_e32 v123, v115, v143
	v_fmac_f32_dpp v116, v148, v156 row_shr:1 row_mask:0xf bank_mask:0xf bound_ctrl:1
	v_fmac_f32_dpp v117, v149, v157 row_shr:1 row_mask:0xf bank_mask:0xf bound_ctrl:1
	v_fmac_f32_dpp v118, v150, v158 row_shr:1 row_mask:0xf bank_mask:0xf bound_ctrl:1
	v_fmac_f32_dpp v119, v151, v159 row_shr:1 row_mask:0xf bank_mask:0xf bound_ctrl:1
	v_fmac_f32_dpp v120, v140, v104 row_shr:1 row_mask:0xf bank_mask:0xf bound_ctrl:1
	v_fmac_f32_dpp v121, v141, v105 row_shr:1 row_mask:0xf bank_mask:0xf bound_ctrl:1
	v_fmac_f32_dpp v122, v142, v106 row_shr:1 row_mask:0xf bank_mask:0xf bound_ctrl:1
	v_fmac_f32_dpp v123, v143, v107 row_shr:1 row_mask:0xf bank_mask:0xf bound_ctrl:1
	v_fmac_f32_dpp v116, v148, v160 row_shl:1 row_mask:0xf bank_mask:0xf bound_ctrl:1
	v_fmac_f32_dpp v117, v149, v161 row_shl:1 row_mask:0xf bank_mask:0xf bound_ctrl:1
	v_fmac_f32_dpp v118, v150, v162 row_shl:1 row_mask:0xf bank_mask:0xf bound_ctrl:1
	v_fmac_f32_dpp v119, v151, v163 row_shl:1 row_mask:0xf bank_mask:0xf bound_ctrl:1
	v_fmac_f32_dpp v120, v140, v108 row_shl:1 row_mask:0xf bank_mask:0xf bound_ctrl:1
	v_fmac_f32_dpp v121, v141, v109 row_shl:1 row_mask:0xf bank_mask:0xf bound_ctrl:1
	v_fmac_f32_dpp v122, v142, v110 row_shl:1 row_mask:0xf bank_mask:0xf bound_ctrl:1
	v_fmac_f32_dpp v123, v143, v111 row_shl:1 row_mask:0xf bank_mask:0xf bound_ctrl:1
	v_fmac_f32_dpp v116, v152, v156 row_shl:15 row_mask:0xf bank_mask:0xf bound_ctrl:1
	v_fmac_f32_dpp v117, v153, v157 row_shl:15 row_mask:0xf bank_mask:0xf bound_ctrl:1
	v_fmac_f32_dpp v118, v154, v158 row_shl:15 row_mask:0xf bank_mask:0xf bound_ctrl:1
	v_fmac_f32_dpp v119, v155, v159 row_shl:15 row_mask:0xf bank_mask:0xf bound_ctrl:1
	v_fmac_f32_dpp v120, v144, v104 row_shl:15 row_mask:0xf bank_mask:0xf bound_ctrl:1
	v_fmac_f32_dpp v121, v145, v105 row_shl:15 row_mask:0xf bank_mask:0xf bound_ctrl:1
	v_fmac_f32_dpp v122, v146, v106 row_shl:15 row_mask:0xf bank_mask:0xf bound_ctrl:1
	v_fmac_f32_dpp v123, v147, v107 row_shl:15 row_mask:0xf bank_mask:0xf bound_ctrl:1
	v_fmac_f32_dpp v116, v136, v160 row_shr:15 row_mask:0xf bank_mask:0xf bound_ctrl:1
	v_fmac_f32_dpp v117, v137, v161 row_shr:15 row_mask:0xf bank_mask:0xf bound_ctrl:1
	v_fmac_f32_dpp v118, v138, v162 row_shr:15 row_mask:0xf bank_mask:0xf bound_ctrl:1
	v_fmac_f32_dpp v119, v139, v163 row_shr:15 row_mask:0xf bank_mask:0xf bound_ctrl:1
	v_fmac_f32_dpp v120, v132, v108 row_shr:15 row_mask:0xf bank_mask:0xf bound_ctrl:1
	v_fmac_f32_dpp v121, v133, v109 row_shr:15 row_mask:0xf bank_mask:0xf bound_ctrl:1
	v_fmac_f32_dpp v122, v134, v110 row_shr:15 row_mask:0xf bank_mask:0xf bound_ctrl:1
	v_fmac_f32_dpp v123, v135, v111 row_shr:15 row_mask:0xf bank_mask:0xf bound_ctrl:1
	v_pk_mul_f32 v[48:49], v[116:117], s[0:1]
	v_pk_mul_f32 v[50:51], v[118:119], s[0:1]
	v_pk_mul_f32 v[52:53], v[116:117], v[120:121]
	v_pk_mul_f32 v[54:55], v[118:119], v[122:123]
	v_exp_f32_e32 v48, v48
	v_exp_f32_e32 v49, v49
	v_exp_f32_e32 v50, v50
	v_exp_f32_e32 v51, v51
	s_nop 0
	v_pk_add_f32 v[48:49], v[48:49], 1.0 op_sel_hi:[1,0]
	v_pk_add_f32 v[50:51], v[50:51], 1.0 op_sel_hi:[1,0]
	v_rcp_f32_e32 v48, v48
	v_rcp_f32_e32 v49, v49
	v_rcp_f32_e32 v50, v50
	v_rcp_f32_e32 v51, v51
	s_nop 0
	v_pk_mul_f32 v[52:53], v[52:53], v[48:49]
	v_pk_mul_f32 v[54:55], v[54:55], v[50:51]
	v_cvt_pk_bf16_f32 v252, v52, v53
	v_cvt_pk_bf16_f32 v253, v54, v55
	global_store_dwordx2 v[244:245], v[252:253], off
	v_lshl_add_u64 v[244:245], v[244:245], 0, s[2:3]
	v_mul_f32_e32 v116, v164, v136
	v_mul_f32_e32 v117, v165, v137
	v_mul_f32_e32 v118, v166, v138
	v_mul_f32_e32 v119, v167, v139
	v_mul_f32_e32 v120, v112, v132
	v_mul_f32_e32 v121, v113, v133
	v_mul_f32_e32 v122, v114, v134
	v_mul_f32_e32 v123, v115, v135
	v_fmac_f32_dpp v116, v136, v156 row_shr:1 row_mask:0xf bank_mask:0xf bound_ctrl:1
	v_fmac_f32_dpp v117, v137, v157 row_shr:1 row_mask:0xf bank_mask:0xf bound_ctrl:1
	v_fmac_f32_dpp v118, v138, v158 row_shr:1 row_mask:0xf bank_mask:0xf bound_ctrl:1
	v_fmac_f32_dpp v119, v139, v159 row_shr:1 row_mask:0xf bank_mask:0xf bound_ctrl:1
	v_fmac_f32_dpp v120, v132, v104 row_shr:1 row_mask:0xf bank_mask:0xf bound_ctrl:1
	v_fmac_f32_dpp v121, v133, v105 row_shr:1 row_mask:0xf bank_mask:0xf bound_ctrl:1
	v_fmac_f32_dpp v122, v134, v106 row_shr:1 row_mask:0xf bank_mask:0xf bound_ctrl:1
	v_fmac_f32_dpp v123, v135, v107 row_shr:1 row_mask:0xf bank_mask:0xf bound_ctrl:1
	v_fmac_f32_dpp v116, v136, v160 row_shl:1 row_mask:0xf bank_mask:0xf bound_ctrl:1
	v_fmac_f32_dpp v117, v137, v161 row_shl:1 row_mask:0xf bank_mask:0xf bound_ctrl:1
	v_fmac_f32_dpp v118, v138, v162 row_shl:1 row_mask:0xf bank_mask:0xf bound_ctrl:1
	v_fmac_f32_dpp v119, v139, v163 row_shl:1 row_mask:0xf bank_mask:0xf bound_ctrl:1
	v_fmac_f32_dpp v120, v132, v108 row_shl:1 row_mask:0xf bank_mask:0xf bound_ctrl:1
	v_fmac_f32_dpp v121, v133, v109 row_shl:1 row_mask:0xf bank_mask:0xf bound_ctrl:1
	v_fmac_f32_dpp v122, v134, v110 row_shl:1 row_mask:0xf bank_mask:0xf bound_ctrl:1
	v_fmac_f32_dpp v123, v135, v111 row_shl:1 row_mask:0xf bank_mask:0xf bound_ctrl:1
	v_fmac_f32_dpp v116, v148, v156 row_shl:15 row_mask:0xf bank_mask:0xf bound_ctrl:1
	v_fmac_f32_dpp v117, v149, v157 row_shl:15 row_mask:0xf bank_mask:0xf bound_ctrl:1
	v_fmac_f32_dpp v118, v150, v158 row_shl:15 row_mask:0xf bank_mask:0xf bound_ctrl:1
	v_fmac_f32_dpp v119, v151, v159 row_shl:15 row_mask:0xf bank_mask:0xf bound_ctrl:1
	v_fmac_f32_dpp v120, v140, v104 row_shl:15 row_mask:0xf bank_mask:0xf bound_ctrl:1
	v_fmac_f32_dpp v121, v141, v105 row_shl:15 row_mask:0xf bank_mask:0xf bound_ctrl:1
	v_fmac_f32_dpp v122, v142, v106 row_shl:15 row_mask:0xf bank_mask:0xf bound_ctrl:1
	v_fmac_f32_dpp v123, v143, v107 row_shl:15 row_mask:0xf bank_mask:0xf bound_ctrl:1
	v_fmac_f32_dpp v116, v128, v160 row_shr:15 row_mask:0xf bank_mask:0xf bound_ctrl:1
	v_fmac_f32_dpp v117, v129, v161 row_shr:15 row_mask:0xf bank_mask:0xf bound_ctrl:1
	v_fmac_f32_dpp v118, v130, v162 row_shr:15 row_mask:0xf bank_mask:0xf bound_ctrl:1
	v_fmac_f32_dpp v119, v131, v163 row_shr:15 row_mask:0xf bank_mask:0xf bound_ctrl:1
	v_fmac_f32_dpp v120, v124, v108 row_shr:15 row_mask:0xf bank_mask:0xf bound_ctrl:1
	v_fmac_f32_dpp v121, v125, v109 row_shr:15 row_mask:0xf bank_mask:0xf bound_ctrl:1
	v_fmac_f32_dpp v122, v126, v110 row_shr:15 row_mask:0xf bank_mask:0xf bound_ctrl:1
	v_fmac_f32_dpp v123, v127, v111 row_shr:15 row_mask:0xf bank_mask:0xf bound_ctrl:1
	v_pk_mul_f32 v[48:49], v[116:117], s[0:1]
	v_pk_mul_f32 v[50:51], v[118:119], s[0:1]
	v_pk_mul_f32 v[52:53], v[116:117], v[120:121]
	v_pk_mul_f32 v[54:55], v[118:119], v[122:123]
	v_exp_f32_e32 v48, v48
	v_exp_f32_e32 v49, v49
	v_exp_f32_e32 v50, v50
	v_exp_f32_e32 v51, v51
	s_nop 0
	v_pk_add_f32 v[48:49], v[48:49], 1.0 op_sel_hi:[1,0]
	v_pk_add_f32 v[50:51], v[50:51], 1.0 op_sel_hi:[1,0]
	v_rcp_f32_e32 v48, v48
	v_rcp_f32_e32 v49, v49
	v_rcp_f32_e32 v50, v50
	v_rcp_f32_e32 v51, v51
	s_nop 0
	v_pk_mul_f32 v[52:53], v[52:53], v[48:49]
	v_pk_mul_f32 v[54:55], v[54:55], v[50:51]
	v_cvt_pk_bf16_f32 v252, v52, v53
	v_cvt_pk_bf16_f32 v253, v54, v55
	global_store_dwordx2 v[244:245], v[252:253], off
	v_lshl_add_u64 v[244:245], v[244:245], 0, s[2:3]
	v_mul_f32_e32 v116, v164, v128
	v_mul_f32_e32 v117, v165, v129
	v_mul_f32_e32 v118, v166, v130
	v_mul_f32_e32 v119, v167, v131
	v_mul_f32_e32 v120, v112, v124
	v_mul_f32_e32 v121, v113, v125
	v_mul_f32_e32 v122, v114, v126
	v_mul_f32_e32 v123, v115, v127
	v_fmac_f32_dpp v116, v128, v156 row_shr:1 row_mask:0xf bank_mask:0xf bound_ctrl:1
	v_fmac_f32_dpp v117, v129, v157 row_shr:1 row_mask:0xf bank_mask:0xf bound_ctrl:1
	v_fmac_f32_dpp v118, v130, v158 row_shr:1 row_mask:0xf bank_mask:0xf bound_ctrl:1
	v_fmac_f32_dpp v119, v131, v159 row_shr:1 row_mask:0xf bank_mask:0xf bound_ctrl:1
	v_fmac_f32_dpp v120, v124, v104 row_shr:1 row_mask:0xf bank_mask:0xf bound_ctrl:1
	v_fmac_f32_dpp v121, v125, v105 row_shr:1 row_mask:0xf bank_mask:0xf bound_ctrl:1
	v_fmac_f32_dpp v122, v126, v106 row_shr:1 row_mask:0xf bank_mask:0xf bound_ctrl:1
	v_fmac_f32_dpp v123, v127, v107 row_shr:1 row_mask:0xf bank_mask:0xf bound_ctrl:1
	v_fmac_f32_dpp v116, v128, v160 row_shl:1 row_mask:0xf bank_mask:0xf bound_ctrl:1
	v_fmac_f32_dpp v117, v129, v161 row_shl:1 row_mask:0xf bank_mask:0xf bound_ctrl:1
	v_fmac_f32_dpp v118, v130, v162 row_shl:1 row_mask:0xf bank_mask:0xf bound_ctrl:1
	v_fmac_f32_dpp v119, v131, v163 row_shl:1 row_mask:0xf bank_mask:0xf bound_ctrl:1
	v_fmac_f32_dpp v120, v124, v108 row_shl:1 row_mask:0xf bank_mask:0xf bound_ctrl:1
	v_fmac_f32_dpp v121, v125, v109 row_shl:1 row_mask:0xf bank_mask:0xf bound_ctrl:1
	v_fmac_f32_dpp v122, v126, v110 row_shl:1 row_mask:0xf bank_mask:0xf bound_ctrl:1
	v_fmac_f32_dpp v123, v127, v111 row_shl:1 row_mask:0xf bank_mask:0xf bound_ctrl:1
	v_fmac_f32_dpp v116, v136, v156 row_shl:15 row_mask:0xf bank_mask:0xf bound_ctrl:1
	v_fmac_f32_dpp v117, v137, v157 row_shl:15 row_mask:0xf bank_mask:0xf bound_ctrl:1
	v_fmac_f32_dpp v118, v138, v158 row_shl:15 row_mask:0xf bank_mask:0xf bound_ctrl:1
	v_fmac_f32_dpp v119, v139, v159 row_shl:15 row_mask:0xf bank_mask:0xf bound_ctrl:1
	v_fmac_f32_dpp v120, v132, v104 row_shl:15 row_mask:0xf bank_mask:0xf bound_ctrl:1
	v_fmac_f32_dpp v121, v133, v105 row_shl:15 row_mask:0xf bank_mask:0xf bound_ctrl:1
	v_fmac_f32_dpp v122, v134, v106 row_shl:15 row_mask:0xf bank_mask:0xf bound_ctrl:1
	v_fmac_f32_dpp v123, v135, v107 row_shl:15 row_mask:0xf bank_mask:0xf bound_ctrl:1
	v_pk_mul_f32 v[48:49], v[116:117], s[0:1]
	v_pk_mul_f32 v[50:51], v[118:119], s[0:1]
	v_pk_mul_f32 v[52:53], v[116:117], v[120:121]
	v_pk_mul_f32 v[54:55], v[118:119], v[122:123]
	v_exp_f32_e32 v48, v48
	v_exp_f32_e32 v49, v49
	v_exp_f32_e32 v50, v50
	v_exp_f32_e32 v51, v51
	v_cvt_pk_bf16_f32 v196, v128, v129
	v_cvt_pk_bf16_f32 v197, v130, v131
	v_cvt_pk_bf16_f32 v198, v124, v125
	v_cvt_pk_bf16_f32 v199, v126, v127
	v_pk_add_f32 v[48:49], v[48:49], 1.0 op_sel_hi:[1,0]
	v_pk_add_f32 v[50:51], v[50:51], 1.0 op_sel_hi:[1,0]
	v_rcp_f32_e32 v48, v48
	v_rcp_f32_e32 v49, v49
	v_rcp_f32_e32 v50, v50
	v_rcp_f32_e32 v51, v51
	s_nop 0
	v_pk_mul_f32 v[52:53], v[52:53], v[48:49]
	v_pk_mul_f32 v[54:55], v[54:55], v[50:51]
	v_cvt_pk_bf16_f32 v252, v52, v53
	v_cvt_pk_bf16_f32 v253, v54, v55
	s_and_saveexec_b64 vcc, s[8:9]
	global_store_dwordx2 v[244:245], v[252:253], off
	s_mov_b64 exec, vcc
	v_add_co_u32_e32 v250, vcc, 0xfffdf000, v250
	s_nop 1
	v_addc_co_u32_e32 v251, vcc, -1, v251, vcc
	v_add_co_u32_e32 v194, vcc, 0x1000, v250
	s_nop 1
	v_addc_co_u32_e32 v195, vcc, 0, v251, vcc
	s_and_saveexec_b64 vcc, s[14:15]
	global_store_dwordx2 v[250:251], v[196:197], off
	global_store_dwordx2 v[194:195], v[198:199], off offset:1536
	s_mov_b64 exec, vcc
	v_add_co_u32_e32 v244, vcc, 0xb0000, v246
	s_nop 1
	v_addc_co_u32_e32 v245, vcc, 0, v247, vcc
	v_add_co_u32_e32 v250, vcc, 0x16000, v248
	s_nop 1
	v_addc_co_u32_e32 v251, vcc, 0, v249, vcc
	v_add_co_u32_e32 v194, vcc, 0x1000, v250
	s_nop 1
	v_addc_co_u32_e32 v195, vcc, 0, v251, vcc
	v_mul_f32_e32 v116, v164, v100
	v_mul_f32_e32 v117, v165, v101
	v_mul_f32_e32 v118, v166, v102
	v_mul_f32_e32 v119, v167, v103
	v_mul_f32_e32 v120, v112, v92
	v_mul_f32_e32 v121, v113, v93
	v_mul_f32_e32 v122, v114, v94
	v_mul_f32_e32 v123, v115, v95
	v_fmac_f32_dpp v116, v100, v156 row_shr:1 row_mask:0xf bank_mask:0xf bound_ctrl:1
	v_fmac_f32_dpp v117, v101, v157 row_shr:1 row_mask:0xf bank_mask:0xf bound_ctrl:1
	v_fmac_f32_dpp v118, v102, v158 row_shr:1 row_mask:0xf bank_mask:0xf bound_ctrl:1
	v_fmac_f32_dpp v119, v103, v159 row_shr:1 row_mask:0xf bank_mask:0xf bound_ctrl:1
	v_fmac_f32_dpp v120, v92, v104 row_shr:1 row_mask:0xf bank_mask:0xf bound_ctrl:1
	v_fmac_f32_dpp v121, v93, v105 row_shr:1 row_mask:0xf bank_mask:0xf bound_ctrl:1
	v_fmac_f32_dpp v122, v94, v106 row_shr:1 row_mask:0xf bank_mask:0xf bound_ctrl:1
	v_fmac_f32_dpp v123, v95, v107 row_shr:1 row_mask:0xf bank_mask:0xf bound_ctrl:1
	v_fmac_f32_dpp v116, v100, v160 row_shl:1 row_mask:0xf bank_mask:0xf bound_ctrl:1
	v_fmac_f32_dpp v117, v101, v161 row_shl:1 row_mask:0xf bank_mask:0xf bound_ctrl:1
	v_fmac_f32_dpp v118, v102, v162 row_shl:1 row_mask:0xf bank_mask:0xf bound_ctrl:1
	v_fmac_f32_dpp v119, v103, v163 row_shl:1 row_mask:0xf bank_mask:0xf bound_ctrl:1
	v_fmac_f32_dpp v120, v92, v108 row_shl:1 row_mask:0xf bank_mask:0xf bound_ctrl:1
	v_fmac_f32_dpp v121, v93, v109 row_shl:1 row_mask:0xf bank_mask:0xf bound_ctrl:1
	v_fmac_f32_dpp v122, v94, v110 row_shl:1 row_mask:0xf bank_mask:0xf bound_ctrl:1
	v_fmac_f32_dpp v123, v95, v111 row_shl:1 row_mask:0xf bank_mask:0xf bound_ctrl:1
	v_fmac_f32_dpp v116, v96, v160 row_shr:15 row_mask:0xf bank_mask:0xf bound_ctrl:1
	v_fmac_f32_dpp v117, v97, v161 row_shr:15 row_mask:0xf bank_mask:0xf bound_ctrl:1
	v_fmac_f32_dpp v118, v98, v162 row_shr:15 row_mask:0xf bank_mask:0xf bound_ctrl:1
	v_fmac_f32_dpp v119, v99, v163 row_shr:15 row_mask:0xf bank_mask:0xf bound_ctrl:1
	v_fmac_f32_dpp v120, v88, v108 row_shr:15 row_mask:0xf bank_mask:0xf bound_ctrl:1
	v_fmac_f32_dpp v121, v89, v109 row_shr:15 row_mask:0xf bank_mask:0xf bound_ctrl:1
	v_fmac_f32_dpp v122, v90, v110 row_shr:15 row_mask:0xf bank_mask:0xf bound_ctrl:1
	v_fmac_f32_dpp v123, v91, v111 row_shr:15 row_mask:0xf bank_mask:0xf bound_ctrl:1
	v_pk_mul_f32 v[48:49], v[116:117], s[0:1]
	v_pk_mul_f32 v[50:51], v[118:119], s[0:1]
	v_pk_mul_f32 v[52:53], v[116:117], v[120:121]
	v_pk_mul_f32 v[54:55], v[118:119], v[122:123]
	v_exp_f32_e32 v48, v48
	v_exp_f32_e32 v49, v49
	v_exp_f32_e32 v50, v50
	v_exp_f32_e32 v51, v51
	v_cvt_pk_bf16_f32 v196, v100, v101
	v_cvt_pk_bf16_f32 v197, v102, v103
	v_cvt_pk_bf16_f32 v198, v92, v93
	v_cvt_pk_bf16_f32 v199, v94, v95
	v_pk_add_f32 v[48:49], v[48:49], 1.0 op_sel_hi:[1,0]
	v_pk_add_f32 v[50:51], v[50:51], 1.0 op_sel_hi:[1,0]
	v_rcp_f32_e32 v48, v48
	v_rcp_f32_e32 v49, v49
	v_rcp_f32_e32 v50, v50
	v_rcp_f32_e32 v51, v51
	s_nop 0
	v_pk_mul_f32 v[52:53], v[52:53], v[48:49]
	v_pk_mul_f32 v[54:55], v[54:55], v[50:51]
	v_cvt_pk_bf16_f32 v252, v52, v53
	v_cvt_pk_bf16_f32 v253, v54, v55
	s_and_saveexec_b64 vcc, s[10:11]
	global_store_dwordx2 v[244:245], v[252:253], off
	s_mov_b64 exec, vcc
	s_and_saveexec_b64 vcc, s[12:13]
	global_store_dwordx2 v[250:251], v[196:197], off
	global_store_dwordx2 v[194:195], v[198:199], off offset:1536
	s_mov_b64 exec, vcc
	v_lshl_add_u64 v[244:245], v[244:245], 0, s[2:3]
	v_mul_f32_e32 v116, v164, v96
	v_mul_f32_e32 v117, v165, v97
	v_mul_f32_e32 v118, v166, v98
	v_mul_f32_e32 v119, v167, v99
	v_mul_f32_e32 v120, v112, v88
	v_mul_f32_e32 v121, v113, v89
	v_mul_f32_e32 v122, v114, v90
	v_mul_f32_e32 v123, v115, v91
	v_fmac_f32_dpp v116, v96, v156 row_shr:1 row_mask:0xf bank_mask:0xf bound_ctrl:1
	v_fmac_f32_dpp v117, v97, v157 row_shr:1 row_mask:0xf bank_mask:0xf bound_ctrl:1
	v_fmac_f32_dpp v118, v98, v158 row_shr:1 row_mask:0xf bank_mask:0xf bound_ctrl:1
	v_fmac_f32_dpp v119, v99, v159 row_shr:1 row_mask:0xf bank_mask:0xf bound_ctrl:1
	v_fmac_f32_dpp v120, v88, v104 row_shr:1 row_mask:0xf bank_mask:0xf bound_ctrl:1
	v_fmac_f32_dpp v121, v89, v105 row_shr:1 row_mask:0xf bank_mask:0xf bound_ctrl:1
	v_fmac_f32_dpp v122, v90, v106 row_shr:1 row_mask:0xf bank_mask:0xf bound_ctrl:1
	v_fmac_f32_dpp v123, v91, v107 row_shr:1 row_mask:0xf bank_mask:0xf bound_ctrl:1
	v_fmac_f32_dpp v116, v96, v160 row_shl:1 row_mask:0xf bank_mask:0xf bound_ctrl:1
	v_fmac_f32_dpp v117, v97, v161 row_shl:1 row_mask:0xf bank_mask:0xf bound_ctrl:1
	v_fmac_f32_dpp v118, v98, v162 row_shl:1 row_mask:0xf bank_mask:0xf bound_ctrl:1
	v_fmac_f32_dpp v119, v99, v163 row_shl:1 row_mask:0xf bank_mask:0xf bound_ctrl:1
	v_fmac_f32_dpp v120, v88, v108 row_shl:1 row_mask:0xf bank_mask:0xf bound_ctrl:1
	v_fmac_f32_dpp v121, v89, v109 row_shl:1 row_mask:0xf bank_mask:0xf bound_ctrl:1
	v_fmac_f32_dpp v122, v90, v110 row_shl:1 row_mask:0xf bank_mask:0xf bound_ctrl:1
	v_fmac_f32_dpp v123, v91, v111 row_shl:1 row_mask:0xf bank_mask:0xf bound_ctrl:1
	v_fmac_f32_dpp v116, v100, v156 row_shl:15 row_mask:0xf bank_mask:0xf bound_ctrl:1
	v_fmac_f32_dpp v117, v101, v157 row_shl:15 row_mask:0xf bank_mask:0xf bound_ctrl:1
	v_fmac_f32_dpp v118, v102, v158 row_shl:15 row_mask:0xf bank_mask:0xf bound_ctrl:1
	v_fmac_f32_dpp v119, v103, v159 row_shl:15 row_mask:0xf bank_mask:0xf bound_ctrl:1
	v_fmac_f32_dpp v120, v92, v104 row_shl:15 row_mask:0xf bank_mask:0xf bound_ctrl:1
	v_fmac_f32_dpp v121, v93, v105 row_shl:15 row_mask:0xf bank_mask:0xf bound_ctrl:1
	v_fmac_f32_dpp v122, v94, v106 row_shl:15 row_mask:0xf bank_mask:0xf bound_ctrl:1
	v_fmac_f32_dpp v123, v95, v107 row_shl:15 row_mask:0xf bank_mask:0xf bound_ctrl:1
	v_fmac_f32_dpp v116, v84, v160 row_shr:15 row_mask:0xf bank_mask:0xf bound_ctrl:1
	v_fmac_f32_dpp v117, v85, v161 row_shr:15 row_mask:0xf bank_mask:0xf bound_ctrl:1
	v_fmac_f32_dpp v118, v86, v162 row_shr:15 row_mask:0xf bank_mask:0xf bound_ctrl:1
	v_fmac_f32_dpp v119, v87, v163 row_shr:15 row_mask:0xf bank_mask:0xf bound_ctrl:1
	v_fmac_f32_dpp v120, v80, v108 row_shr:15 row_mask:0xf bank_mask:0xf bound_ctrl:1
	v_fmac_f32_dpp v121, v81, v109 row_shr:15 row_mask:0xf bank_mask:0xf bound_ctrl:1
	v_fmac_f32_dpp v122, v82, v110 row_shr:15 row_mask:0xf bank_mask:0xf bound_ctrl:1
	v_fmac_f32_dpp v123, v83, v111 row_shr:15 row_mask:0xf bank_mask:0xf bound_ctrl:1
	v_pk_mul_f32 v[48:49], v[116:117], s[0:1]
	v_pk_mul_f32 v[50:51], v[118:119], s[0:1]
	v_pk_mul_f32 v[52:53], v[116:117], v[120:121]
	v_pk_mul_f32 v[54:55], v[118:119], v[122:123]
	v_exp_f32_e32 v48, v48
	v_exp_f32_e32 v49, v49
	v_exp_f32_e32 v50, v50
	v_exp_f32_e32 v51, v51
	s_nop 0
	v_pk_add_f32 v[48:49], v[48:49], 1.0 op_sel_hi:[1,0]
	v_pk_add_f32 v[50:51], v[50:51], 1.0 op_sel_hi:[1,0]
	v_rcp_f32_e32 v48, v48
	v_rcp_f32_e32 v49, v49
	v_rcp_f32_e32 v50, v50
	v_rcp_f32_e32 v51, v51
	s_nop 0
	v_pk_mul_f32 v[52:53], v[52:53], v[48:49]
	v_pk_mul_f32 v[54:55], v[54:55], v[50:51]
	v_cvt_pk_bf16_f32 v252, v52, v53
	v_cvt_pk_bf16_f32 v253, v54, v55
	global_store_dwordx2 v[244:245], v[252:253], off
	v_lshl_add_u64 v[244:245], v[244:245], 0, s[2:3]
	v_mul_f32_e32 v116, v164, v84
	v_mul_f32_e32 v117, v165, v85
	v_mul_f32_e32 v118, v166, v86
	v_mul_f32_e32 v119, v167, v87
	v_mul_f32_e32 v120, v112, v80
	v_mul_f32_e32 v121, v113, v81
	v_mul_f32_e32 v122, v114, v82
	v_mul_f32_e32 v123, v115, v83
	v_fmac_f32_dpp v116, v84, v156 row_shr:1 row_mask:0xf bank_mask:0xf bound_ctrl:1
	v_fmac_f32_dpp v117, v85, v157 row_shr:1 row_mask:0xf bank_mask:0xf bound_ctrl:1
	v_fmac_f32_dpp v118, v86, v158 row_shr:1 row_mask:0xf bank_mask:0xf bound_ctrl:1
	v_fmac_f32_dpp v119, v87, v159 row_shr:1 row_mask:0xf bank_mask:0xf bound_ctrl:1
	v_fmac_f32_dpp v120, v80, v104 row_shr:1 row_mask:0xf bank_mask:0xf bound_ctrl:1
	v_fmac_f32_dpp v121, v81, v105 row_shr:1 row_mask:0xf bank_mask:0xf bound_ctrl:1
	v_fmac_f32_dpp v122, v82, v106 row_shr:1 row_mask:0xf bank_mask:0xf bound_ctrl:1
	v_fmac_f32_dpp v123, v83, v107 row_shr:1 row_mask:0xf bank_mask:0xf bound_ctrl:1
	v_fmac_f32_dpp v116, v84, v160 row_shl:1 row_mask:0xf bank_mask:0xf bound_ctrl:1
	v_fmac_f32_dpp v117, v85, v161 row_shl:1 row_mask:0xf bank_mask:0xf bound_ctrl:1
	v_fmac_f32_dpp v118, v86, v162 row_shl:1 row_mask:0xf bank_mask:0xf bound_ctrl:1
	v_fmac_f32_dpp v119, v87, v163 row_shl:1 row_mask:0xf bank_mask:0xf bound_ctrl:1
	v_fmac_f32_dpp v120, v80, v108 row_shl:1 row_mask:0xf bank_mask:0xf bound_ctrl:1
	v_fmac_f32_dpp v121, v81, v109 row_shl:1 row_mask:0xf bank_mask:0xf bound_ctrl:1
	v_fmac_f32_dpp v122, v82, v110 row_shl:1 row_mask:0xf bank_mask:0xf bound_ctrl:1
	v_fmac_f32_dpp v123, v83, v111 row_shl:1 row_mask:0xf bank_mask:0xf bound_ctrl:1
	v_fmac_f32_dpp v116, v96, v156 row_shl:15 row_mask:0xf bank_mask:0xf bound_ctrl:1
	v_fmac_f32_dpp v117, v97, v157 row_shl:15 row_mask:0xf bank_mask:0xf bound_ctrl:1
	v_fmac_f32_dpp v118, v98, v158 row_shl:15 row_mask:0xf bank_mask:0xf bound_ctrl:1
	v_fmac_f32_dpp v119, v99, v159 row_shl:15 row_mask:0xf bank_mask:0xf bound_ctrl:1
	v_fmac_f32_dpp v120, v88, v104 row_shl:15 row_mask:0xf bank_mask:0xf bound_ctrl:1
	v_fmac_f32_dpp v121, v89, v105 row_shl:15 row_mask:0xf bank_mask:0xf bound_ctrl:1
	v_fmac_f32_dpp v122, v90, v106 row_shl:15 row_mask:0xf bank_mask:0xf bound_ctrl:1
	v_fmac_f32_dpp v123, v91, v107 row_shl:15 row_mask:0xf bank_mask:0xf bound_ctrl:1
	v_fmac_f32_dpp v116, v76, v160 row_shr:15 row_mask:0xf bank_mask:0xf bound_ctrl:1
	v_fmac_f32_dpp v117, v77, v161 row_shr:15 row_mask:0xf bank_mask:0xf bound_ctrl:1
	v_fmac_f32_dpp v118, v78, v162 row_shr:15 row_mask:0xf bank_mask:0xf bound_ctrl:1
	v_fmac_f32_dpp v119, v79, v163 row_shr:15 row_mask:0xf bank_mask:0xf bound_ctrl:1
	v_fmac_f32_dpp v120, v72, v108 row_shr:15 row_mask:0xf bank_mask:0xf bound_ctrl:1
	v_fmac_f32_dpp v121, v73, v109 row_shr:15 row_mask:0xf bank_mask:0xf bound_ctrl:1
	v_fmac_f32_dpp v122, v74, v110 row_shr:15 row_mask:0xf bank_mask:0xf bound_ctrl:1
	v_fmac_f32_dpp v123, v75, v111 row_shr:15 row_mask:0xf bank_mask:0xf bound_ctrl:1
	v_pk_mul_f32 v[48:49], v[116:117], s[0:1]
	v_pk_mul_f32 v[50:51], v[118:119], s[0:1]
	v_pk_mul_f32 v[52:53], v[116:117], v[120:121]
	v_pk_mul_f32 v[54:55], v[118:119], v[122:123]
	v_exp_f32_e32 v48, v48
	v_exp_f32_e32 v49, v49
	v_exp_f32_e32 v50, v50
	v_exp_f32_e32 v51, v51
	s_nop 0
	v_pk_add_f32 v[48:49], v[48:49], 1.0 op_sel_hi:[1,0]
	v_pk_add_f32 v[50:51], v[50:51], 1.0 op_sel_hi:[1,0]
	v_rcp_f32_e32 v48, v48
	v_rcp_f32_e32 v49, v49
	v_rcp_f32_e32 v50, v50
	v_rcp_f32_e32 v51, v51
	s_nop 0
	v_pk_mul_f32 v[52:53], v[52:53], v[48:49]
	v_pk_mul_f32 v[54:55], v[54:55], v[50:51]
	v_cvt_pk_bf16_f32 v252, v52, v53
	v_cvt_pk_bf16_f32 v253, v54, v55
	global_store_dwordx2 v[244:245], v[252:253], off
	v_lshl_add_u64 v[244:245], v[244:245], 0, s[2:3]
	v_mul_f32_e32 v116, v164, v76
	v_mul_f32_e32 v117, v165, v77
	v_mul_f32_e32 v118, v166, v78
	v_mul_f32_e32 v119, v167, v79
	v_mul_f32_e32 v120, v112, v72
	v_mul_f32_e32 v121, v113, v73
	v_mul_f32_e32 v122, v114, v74
	v_mul_f32_e32 v123, v115, v75
	v_fmac_f32_dpp v116, v76, v156 row_shr:1 row_mask:0xf bank_mask:0xf bound_ctrl:1
	v_fmac_f32_dpp v117, v77, v157 row_shr:1 row_mask:0xf bank_mask:0xf bound_ctrl:1
	v_fmac_f32_dpp v118, v78, v158 row_shr:1 row_mask:0xf bank_mask:0xf bound_ctrl:1
	v_fmac_f32_dpp v119, v79, v159 row_shr:1 row_mask:0xf bank_mask:0xf bound_ctrl:1
	v_fmac_f32_dpp v120, v72, v104 row_shr:1 row_mask:0xf bank_mask:0xf bound_ctrl:1
	v_fmac_f32_dpp v121, v73, v105 row_shr:1 row_mask:0xf bank_mask:0xf bound_ctrl:1
	v_fmac_f32_dpp v122, v74, v106 row_shr:1 row_mask:0xf bank_mask:0xf bound_ctrl:1
	v_fmac_f32_dpp v123, v75, v107 row_shr:1 row_mask:0xf bank_mask:0xf bound_ctrl:1
	v_fmac_f32_dpp v116, v76, v160 row_shl:1 row_mask:0xf bank_mask:0xf bound_ctrl:1
	v_fmac_f32_dpp v117, v77, v161 row_shl:1 row_mask:0xf bank_mask:0xf bound_ctrl:1
	v_fmac_f32_dpp v118, v78, v162 row_shl:1 row_mask:0xf bank_mask:0xf bound_ctrl:1
	v_fmac_f32_dpp v119, v79, v163 row_shl:1 row_mask:0xf bank_mask:0xf bound_ctrl:1
	v_fmac_f32_dpp v120, v72, v108 row_shl:1 row_mask:0xf bank_mask:0xf bound_ctrl:1
	v_fmac_f32_dpp v121, v73, v109 row_shl:1 row_mask:0xf bank_mask:0xf bound_ctrl:1
	v_fmac_f32_dpp v122, v74, v110 row_shl:1 row_mask:0xf bank_mask:0xf bound_ctrl:1
	v_fmac_f32_dpp v123, v75, v111 row_shl:1 row_mask:0xf bank_mask:0xf bound_ctrl:1
	v_fmac_f32_dpp v116, v84, v156 row_shl:15 row_mask:0xf bank_mask:0xf bound_ctrl:1
	v_fmac_f32_dpp v117, v85, v157 row_shl:15 row_mask:0xf bank_mask:0xf bound_ctrl:1
	v_fmac_f32_dpp v118, v86, v158 row_shl:15 row_mask:0xf bank_mask:0xf bound_ctrl:1
	v_fmac_f32_dpp v119, v87, v159 row_shl:15 row_mask:0xf bank_mask:0xf bound_ctrl:1
	v_fmac_f32_dpp v120, v80, v104 row_shl:15 row_mask:0xf bank_mask:0xf bound_ctrl:1
	v_fmac_f32_dpp v121, v81, v105 row_shl:15 row_mask:0xf bank_mask:0xf bound_ctrl:1
	v_fmac_f32_dpp v122, v82, v106 row_shl:15 row_mask:0xf bank_mask:0xf bound_ctrl:1
	v_fmac_f32_dpp v123, v83, v107 row_shl:15 row_mask:0xf bank_mask:0xf bound_ctrl:1
	v_pk_mul_f32 v[48:49], v[116:117], s[0:1]
	v_pk_mul_f32 v[50:51], v[118:119], s[0:1]
	v_pk_mul_f32 v[52:53], v[116:117], v[120:121]
	v_pk_mul_f32 v[54:55], v[118:119], v[122:123]
	v_exp_f32_e32 v48, v48
	v_exp_f32_e32 v49, v49
	v_exp_f32_e32 v50, v50
	v_exp_f32_e32 v51, v51
	v_cvt_pk_bf16_f32 v196, v76, v77
	v_cvt_pk_bf16_f32 v197, v78, v79
	v_cvt_pk_bf16_f32 v198, v72, v73
	v_cvt_pk_bf16_f32 v199, v74, v75
	v_pk_add_f32 v[48:49], v[48:49], 1.0 op_sel_hi:[1,0]
	v_pk_add_f32 v[50:51], v[50:51], 1.0 op_sel_hi:[1,0]
	v_rcp_f32_e32 v48, v48
	v_rcp_f32_e32 v49, v49
	v_rcp_f32_e32 v50, v50
	v_rcp_f32_e32 v51, v51
	s_nop 0
	v_pk_mul_f32 v[52:53], v[52:53], v[48:49]
	v_pk_mul_f32 v[54:55], v[54:55], v[50:51]
	v_cvt_pk_bf16_f32 v252, v52, v53
	v_cvt_pk_bf16_f32 v253, v54, v55
	s_and_saveexec_b64 vcc, s[8:9]
	global_store_dwordx2 v[244:245], v[252:253], off
	s_mov_b64 exec, vcc
	v_add_co_u32_e32 v250, vcc, 0xfffdf000, v250
	s_nop 1
	v_addc_co_u32_e32 v251, vcc, -1, v251, vcc
	v_add_co_u32_e32 v194, vcc, 0x1000, v250
	s_nop 1
	v_addc_co_u32_e32 v195, vcc, 0, v251, vcc
	s_and_saveexec_b64 vcc, s[14:15]
	global_store_dwordx2 v[250:251], v[196:197], off
	global_store_dwordx2 v[194:195], v[198:199], off offset:1536
	s_mov_b64 exec, vcc
	v_mov_b32_e32 v244, v246
	v_mov_b32_e32 v245, v247
	v_mov_b32_e32 v250, v248
	v_mov_b32_e32 v251, v249
	v_add_co_u32_e32 v194, vcc, 0x1000, v250
	s_nop 1
	v_addc_co_u32_e32 v195, vcc, 0, v251, vcc
	v_mul_f32_e32 v116, v208, v68
	v_mul_f32_e32 v117, v209, v69
	v_mul_f32_e32 v118, v210, v70
	v_mul_f32_e32 v119, v211, v71
	v_mul_f32_e32 v120, v212, v60
	v_mul_f32_e32 v121, v213, v61
	v_mul_f32_e32 v122, v214, v62
	v_mul_f32_e32 v123, v215, v63
	v_fmac_f32_dpp v116, v68, v220 row_shr:1 row_mask:0xf bank_mask:0xf bound_ctrl:1
	v_fmac_f32_dpp v117, v69, v221 row_shr:1 row_mask:0xf bank_mask:0xf bound_ctrl:1
	v_fmac_f32_dpp v118, v70, v222 row_shr:1 row_mask:0xf bank_mask:0xf bound_ctrl:1
	v_fmac_f32_dpp v119, v71, v223 row_shr:1 row_mask:0xf bank_mask:0xf bound_ctrl:1
	v_fmac_f32_dpp v120, v60, v204 row_shr:1 row_mask:0xf bank_mask:0xf bound_ctrl:1
	v_fmac_f32_dpp v121, v61, v205 row_shr:1 row_mask:0xf bank_mask:0xf bound_ctrl:1
	v_fmac_f32_dpp v122, v62, v206 row_shr:1 row_mask:0xf bank_mask:0xf bound_ctrl:1
	v_fmac_f32_dpp v123, v63, v207 row_shr:1 row_mask:0xf bank_mask:0xf bound_ctrl:1
	v_fmac_f32_dpp v116, v68, v216 row_shl:1 row_mask:0xf bank_mask:0xf bound_ctrl:1
	v_fmac_f32_dpp v117, v69, v217 row_shl:1 row_mask:0xf bank_mask:0xf bound_ctrl:1
	v_fmac_f32_dpp v118, v70, v218 row_shl:1 row_mask:0xf bank_mask:0xf bound_ctrl:1
	v_fmac_f32_dpp v119, v71, v219 row_shl:1 row_mask:0xf bank_mask:0xf bound_ctrl:1
	v_fmac_f32_dpp v120, v60, v200 row_shl:1 row_mask:0xf bank_mask:0xf bound_ctrl:1
	v_fmac_f32_dpp v121, v61, v201 row_shl:1 row_mask:0xf bank_mask:0xf bound_ctrl:1
	v_fmac_f32_dpp v122, v62, v202 row_shl:1 row_mask:0xf bank_mask:0xf bound_ctrl:1
	v_fmac_f32_dpp v123, v63, v203 row_shl:1 row_mask:0xf bank_mask:0xf bound_ctrl:1
	v_fmac_f32_dpp v116, v64, v216 row_shr:15 row_mask:0xf bank_mask:0xf bound_ctrl:1
	v_fmac_f32_dpp v117, v65, v217 row_shr:15 row_mask:0xf bank_mask:0xf bound_ctrl:1
	v_fmac_f32_dpp v118, v66, v218 row_shr:15 row_mask:0xf bank_mask:0xf bound_ctrl:1
	v_fmac_f32_dpp v119, v67, v219 row_shr:15 row_mask:0xf bank_mask:0xf bound_ctrl:1
	v_fmac_f32_dpp v120, v56, v200 row_shr:15 row_mask:0xf bank_mask:0xf bound_ctrl:1
	v_fmac_f32_dpp v121, v57, v201 row_shr:15 row_mask:0xf bank_mask:0xf bound_ctrl:1
	v_fmac_f32_dpp v122, v58, v202 row_shr:15 row_mask:0xf bank_mask:0xf bound_ctrl:1
	v_fmac_f32_dpp v123, v59, v203 row_shr:15 row_mask:0xf bank_mask:0xf bound_ctrl:1
	v_pk_mul_f32 v[48:49], v[116:117], s[0:1]
	v_pk_mul_f32 v[50:51], v[118:119], s[0:1]
	v_pk_mul_f32 v[52:53], v[116:117], v[120:121]
	v_pk_mul_f32 v[54:55], v[118:119], v[122:123]
	v_exp_f32_e32 v48, v48
	v_exp_f32_e32 v49, v49
	v_exp_f32_e32 v50, v50
	v_exp_f32_e32 v51, v51
	v_cvt_pk_bf16_f32 v196, v68, v69
	v_cvt_pk_bf16_f32 v197, v70, v71
	v_cvt_pk_bf16_f32 v198, v60, v61
	v_cvt_pk_bf16_f32 v199, v62, v63
	v_pk_add_f32 v[48:49], v[48:49], 1.0 op_sel_hi:[1,0]
	v_pk_add_f32 v[50:51], v[50:51], 1.0 op_sel_hi:[1,0]
	v_rcp_f32_e32 v48, v48
	v_rcp_f32_e32 v49, v49
	v_rcp_f32_e32 v50, v50
	v_rcp_f32_e32 v51, v51
	s_nop 0
	v_pk_mul_f32 v[52:53], v[52:53], v[48:49]
	v_pk_mul_f32 v[54:55], v[54:55], v[50:51]
	v_cvt_pk_bf16_f32 v252, v52, v53
	v_cvt_pk_bf16_f32 v253, v54, v55
	s_and_saveexec_b64 vcc, s[10:11]
	global_store_dwordx2 v[244:245], v[252:253], off offset:8
	s_mov_b64 exec, vcc
	s_and_saveexec_b64 vcc, s[12:13]
	global_store_dwordx2 v[250:251], v[196:197], off offset:8
	global_store_dwordx2 v[194:195], v[198:199], off offset:1544
	s_mov_b64 exec, vcc
	v_lshl_add_u64 v[244:245], v[244:245], 0, s[2:3]
	v_mul_f32_e32 v116, v208, v64
	v_mul_f32_e32 v117, v209, v65
	v_mul_f32_e32 v118, v210, v66
	v_mul_f32_e32 v119, v211, v67
	v_mul_f32_e32 v120, v212, v56
	v_mul_f32_e32 v121, v213, v57
	v_mul_f32_e32 v122, v214, v58
	v_mul_f32_e32 v123, v215, v59
	v_fmac_f32_dpp v116, v64, v220 row_shr:1 row_mask:0xf bank_mask:0xf bound_ctrl:1
	v_fmac_f32_dpp v117, v65, v221 row_shr:1 row_mask:0xf bank_mask:0xf bound_ctrl:1
	v_fmac_f32_dpp v118, v66, v222 row_shr:1 row_mask:0xf bank_mask:0xf bound_ctrl:1
	v_fmac_f32_dpp v119, v67, v223 row_shr:1 row_mask:0xf bank_mask:0xf bound_ctrl:1
	v_fmac_f32_dpp v120, v56, v204 row_shr:1 row_mask:0xf bank_mask:0xf bound_ctrl:1
	v_fmac_f32_dpp v121, v57, v205 row_shr:1 row_mask:0xf bank_mask:0xf bound_ctrl:1
	v_fmac_f32_dpp v122, v58, v206 row_shr:1 row_mask:0xf bank_mask:0xf bound_ctrl:1
	v_fmac_f32_dpp v123, v59, v207 row_shr:1 row_mask:0xf bank_mask:0xf bound_ctrl:1
	v_fmac_f32_dpp v116, v64, v216 row_shl:1 row_mask:0xf bank_mask:0xf bound_ctrl:1
	v_fmac_f32_dpp v117, v65, v217 row_shl:1 row_mask:0xf bank_mask:0xf bound_ctrl:1
	v_fmac_f32_dpp v118, v66, v218 row_shl:1 row_mask:0xf bank_mask:0xf bound_ctrl:1
	v_fmac_f32_dpp v119, v67, v219 row_shl:1 row_mask:0xf bank_mask:0xf bound_ctrl:1
	v_fmac_f32_dpp v120, v56, v200 row_shl:1 row_mask:0xf bank_mask:0xf bound_ctrl:1
	v_fmac_f32_dpp v121, v57, v201 row_shl:1 row_mask:0xf bank_mask:0xf bound_ctrl:1
	v_fmac_f32_dpp v122, v58, v202 row_shl:1 row_mask:0xf bank_mask:0xf bound_ctrl:1
	v_fmac_f32_dpp v123, v59, v203 row_shl:1 row_mask:0xf bank_mask:0xf bound_ctrl:1
	v_fmac_f32_dpp v116, v68, v220 row_shl:15 row_mask:0xf bank_mask:0xf bound_ctrl:1
	v_fmac_f32_dpp v117, v69, v221 row_shl:15 row_mask:0xf bank_mask:0xf bound_ctrl:1
	v_fmac_f32_dpp v118, v70, v222 row_shl:15 row_mask:0xf bank_mask:0xf bound_ctrl:1
	v_fmac_f32_dpp v119, v71, v223 row_shl:15 row_mask:0xf bank_mask:0xf bound_ctrl:1
	v_fmac_f32_dpp v120, v60, v204 row_shl:15 row_mask:0xf bank_mask:0xf bound_ctrl:1
	v_fmac_f32_dpp v121, v61, v205 row_shl:15 row_mask:0xf bank_mask:0xf bound_ctrl:1
	v_fmac_f32_dpp v122, v62, v206 row_shl:15 row_mask:0xf bank_mask:0xf bound_ctrl:1
	v_fmac_f32_dpp v123, v63, v207 row_shl:15 row_mask:0xf bank_mask:0xf bound_ctrl:1
	v_fmac_f32_dpp v116, v44, v216 row_shr:15 row_mask:0xf bank_mask:0xf bound_ctrl:1
	v_fmac_f32_dpp v117, v45, v217 row_shr:15 row_mask:0xf bank_mask:0xf bound_ctrl:1
	v_fmac_f32_dpp v118, v46, v218 row_shr:15 row_mask:0xf bank_mask:0xf bound_ctrl:1
	v_fmac_f32_dpp v119, v47, v219 row_shr:15 row_mask:0xf bank_mask:0xf bound_ctrl:1
	v_fmac_f32_dpp v120, v36, v200 row_shr:15 row_mask:0xf bank_mask:0xf bound_ctrl:1
	v_fmac_f32_dpp v121, v37, v201 row_shr:15 row_mask:0xf bank_mask:0xf bound_ctrl:1
	v_fmac_f32_dpp v122, v38, v202 row_shr:15 row_mask:0xf bank_mask:0xf bound_ctrl:1
	v_fmac_f32_dpp v123, v39, v203 row_shr:15 row_mask:0xf bank_mask:0xf bound_ctrl:1
	v_pk_mul_f32 v[48:49], v[116:117], s[0:1]
	v_pk_mul_f32 v[50:51], v[118:119], s[0:1]
	v_pk_mul_f32 v[52:53], v[116:117], v[120:121]
	v_pk_mul_f32 v[54:55], v[118:119], v[122:123]
	v_exp_f32_e32 v48, v48
	v_exp_f32_e32 v49, v49
	v_exp_f32_e32 v50, v50
	v_exp_f32_e32 v51, v51
	s_nop 0
	v_pk_add_f32 v[48:49], v[48:49], 1.0 op_sel_hi:[1,0]
	v_pk_add_f32 v[50:51], v[50:51], 1.0 op_sel_hi:[1,0]
	v_rcp_f32_e32 v48, v48
	v_rcp_f32_e32 v49, v49
	v_rcp_f32_e32 v50, v50
	v_rcp_f32_e32 v51, v51
	s_nop 0
	v_pk_mul_f32 v[52:53], v[52:53], v[48:49]
	v_pk_mul_f32 v[54:55], v[54:55], v[50:51]
	v_cvt_pk_bf16_f32 v252, v52, v53
	v_cvt_pk_bf16_f32 v253, v54, v55
	global_store_dwordx2 v[244:245], v[252:253], off offset:8
	v_lshl_add_u64 v[244:245], v[244:245], 0, s[2:3]
	v_mul_f32_e32 v116, v208, v44
	v_mul_f32_e32 v117, v209, v45
	v_mul_f32_e32 v118, v210, v46
	v_mul_f32_e32 v119, v211, v47
	v_mul_f32_e32 v120, v212, v36
	v_mul_f32_e32 v121, v213, v37
	v_mul_f32_e32 v122, v214, v38
	v_mul_f32_e32 v123, v215, v39
	v_fmac_f32_dpp v116, v44, v220 row_shr:1 row_mask:0xf bank_mask:0xf bound_ctrl:1
	v_fmac_f32_dpp v117, v45, v221 row_shr:1 row_mask:0xf bank_mask:0xf bound_ctrl:1
	v_fmac_f32_dpp v118, v46, v222 row_shr:1 row_mask:0xf bank_mask:0xf bound_ctrl:1
	v_fmac_f32_dpp v119, v47, v223 row_shr:1 row_mask:0xf bank_mask:0xf bound_ctrl:1
	v_fmac_f32_dpp v120, v36, v204 row_shr:1 row_mask:0xf bank_mask:0xf bound_ctrl:1
	v_fmac_f32_dpp v121, v37, v205 row_shr:1 row_mask:0xf bank_mask:0xf bound_ctrl:1
	v_fmac_f32_dpp v122, v38, v206 row_shr:1 row_mask:0xf bank_mask:0xf bound_ctrl:1
	v_fmac_f32_dpp v123, v39, v207 row_shr:1 row_mask:0xf bank_mask:0xf bound_ctrl:1
	v_fmac_f32_dpp v116, v44, v216 row_shl:1 row_mask:0xf bank_mask:0xf bound_ctrl:1
	v_fmac_f32_dpp v117, v45, v217 row_shl:1 row_mask:0xf bank_mask:0xf bound_ctrl:1
	v_fmac_f32_dpp v118, v46, v218 row_shl:1 row_mask:0xf bank_mask:0xf bound_ctrl:1
	v_fmac_f32_dpp v119, v47, v219 row_shl:1 row_mask:0xf bank_mask:0xf bound_ctrl:1
	v_fmac_f32_dpp v120, v36, v200 row_shl:1 row_mask:0xf bank_mask:0xf bound_ctrl:1
	v_fmac_f32_dpp v121, v37, v201 row_shl:1 row_mask:0xf bank_mask:0xf bound_ctrl:1
	v_fmac_f32_dpp v122, v38, v202 row_shl:1 row_mask:0xf bank_mask:0xf bound_ctrl:1
	v_fmac_f32_dpp v123, v39, v203 row_shl:1 row_mask:0xf bank_mask:0xf bound_ctrl:1
	v_fmac_f32_dpp v116, v64, v220 row_shl:15 row_mask:0xf bank_mask:0xf bound_ctrl:1
	v_fmac_f32_dpp v117, v65, v221 row_shl:15 row_mask:0xf bank_mask:0xf bound_ctrl:1
	v_fmac_f32_dpp v118, v66, v222 row_shl:15 row_mask:0xf bank_mask:0xf bound_ctrl:1
	v_fmac_f32_dpp v119, v67, v223 row_shl:15 row_mask:0xf bank_mask:0xf bound_ctrl:1
	v_fmac_f32_dpp v120, v56, v204 row_shl:15 row_mask:0xf bank_mask:0xf bound_ctrl:1
	v_fmac_f32_dpp v121, v57, v205 row_shl:15 row_mask:0xf bank_mask:0xf bound_ctrl:1
	v_fmac_f32_dpp v122, v58, v206 row_shl:15 row_mask:0xf bank_mask:0xf bound_ctrl:1
	v_fmac_f32_dpp v123, v59, v207 row_shl:15 row_mask:0xf bank_mask:0xf bound_ctrl:1
	v_fmac_f32_dpp v116, v40, v216 row_shr:15 row_mask:0xf bank_mask:0xf bound_ctrl:1
	v_fmac_f32_dpp v117, v41, v217 row_shr:15 row_mask:0xf bank_mask:0xf bound_ctrl:1
	v_fmac_f32_dpp v118, v42, v218 row_shr:15 row_mask:0xf bank_mask:0xf bound_ctrl:1
	v_fmac_f32_dpp v119, v43, v219 row_shr:15 row_mask:0xf bank_mask:0xf bound_ctrl:1
	v_fmac_f32_dpp v120, v32, v200 row_shr:15 row_mask:0xf bank_mask:0xf bound_ctrl:1
	v_fmac_f32_dpp v121, v33, v201 row_shr:15 row_mask:0xf bank_mask:0xf bound_ctrl:1
	v_fmac_f32_dpp v122, v34, v202 row_shr:15 row_mask:0xf bank_mask:0xf bound_ctrl:1
	v_fmac_f32_dpp v123, v35, v203 row_shr:15 row_mask:0xf bank_mask:0xf bound_ctrl:1
	v_pk_mul_f32 v[48:49], v[116:117], s[0:1]
	v_pk_mul_f32 v[50:51], v[118:119], s[0:1]
	v_pk_mul_f32 v[52:53], v[116:117], v[120:121]
	v_pk_mul_f32 v[54:55], v[118:119], v[122:123]
	v_exp_f32_e32 v48, v48
	v_exp_f32_e32 v49, v49
	v_exp_f32_e32 v50, v50
	v_exp_f32_e32 v51, v51
	s_nop 0
	v_pk_add_f32 v[48:49], v[48:49], 1.0 op_sel_hi:[1,0]
	v_pk_add_f32 v[50:51], v[50:51], 1.0 op_sel_hi:[1,0]
	v_rcp_f32_e32 v48, v48
	v_rcp_f32_e32 v49, v49
	v_rcp_f32_e32 v50, v50
	v_rcp_f32_e32 v51, v51
	s_nop 0
	v_pk_mul_f32 v[52:53], v[52:53], v[48:49]
	v_pk_mul_f32 v[54:55], v[54:55], v[50:51]
	v_cvt_pk_bf16_f32 v252, v52, v53
	v_cvt_pk_bf16_f32 v253, v54, v55
	global_store_dwordx2 v[244:245], v[252:253], off offset:8
	v_lshl_add_u64 v[244:245], v[244:245], 0, s[2:3]
	v_mul_f32_e32 v116, v208, v40
	v_mul_f32_e32 v117, v209, v41
	v_mul_f32_e32 v118, v210, v42
	v_mul_f32_e32 v119, v211, v43
	v_mul_f32_e32 v120, v212, v32
	v_mul_f32_e32 v121, v213, v33
	v_mul_f32_e32 v122, v214, v34
	v_mul_f32_e32 v123, v215, v35
	v_fmac_f32_dpp v116, v40, v220 row_shr:1 row_mask:0xf bank_mask:0xf bound_ctrl:1
	v_fmac_f32_dpp v117, v41, v221 row_shr:1 row_mask:0xf bank_mask:0xf bound_ctrl:1
	v_fmac_f32_dpp v118, v42, v222 row_shr:1 row_mask:0xf bank_mask:0xf bound_ctrl:1
	v_fmac_f32_dpp v119, v43, v223 row_shr:1 row_mask:0xf bank_mask:0xf bound_ctrl:1
	v_fmac_f32_dpp v120, v32, v204 row_shr:1 row_mask:0xf bank_mask:0xf bound_ctrl:1
	v_fmac_f32_dpp v121, v33, v205 row_shr:1 row_mask:0xf bank_mask:0xf bound_ctrl:1
	v_fmac_f32_dpp v122, v34, v206 row_shr:1 row_mask:0xf bank_mask:0xf bound_ctrl:1
	v_fmac_f32_dpp v123, v35, v207 row_shr:1 row_mask:0xf bank_mask:0xf bound_ctrl:1
	v_fmac_f32_dpp v116, v40, v216 row_shl:1 row_mask:0xf bank_mask:0xf bound_ctrl:1
	v_fmac_f32_dpp v117, v41, v217 row_shl:1 row_mask:0xf bank_mask:0xf bound_ctrl:1
	v_fmac_f32_dpp v118, v42, v218 row_shl:1 row_mask:0xf bank_mask:0xf bound_ctrl:1
	v_fmac_f32_dpp v119, v43, v219 row_shl:1 row_mask:0xf bank_mask:0xf bound_ctrl:1
	v_fmac_f32_dpp v120, v32, v200 row_shl:1 row_mask:0xf bank_mask:0xf bound_ctrl:1
	v_fmac_f32_dpp v121, v33, v201 row_shl:1 row_mask:0xf bank_mask:0xf bound_ctrl:1
	v_fmac_f32_dpp v122, v34, v202 row_shl:1 row_mask:0xf bank_mask:0xf bound_ctrl:1
	v_fmac_f32_dpp v123, v35, v203 row_shl:1 row_mask:0xf bank_mask:0xf bound_ctrl:1
	v_fmac_f32_dpp v116, v44, v220 row_shl:15 row_mask:0xf bank_mask:0xf bound_ctrl:1
	v_fmac_f32_dpp v117, v45, v221 row_shl:15 row_mask:0xf bank_mask:0xf bound_ctrl:1
	v_fmac_f32_dpp v118, v46, v222 row_shl:15 row_mask:0xf bank_mask:0xf bound_ctrl:1
	v_fmac_f32_dpp v119, v47, v223 row_shl:15 row_mask:0xf bank_mask:0xf bound_ctrl:1
	v_fmac_f32_dpp v120, v36, v204 row_shl:15 row_mask:0xf bank_mask:0xf bound_ctrl:1
	v_fmac_f32_dpp v121, v37, v205 row_shl:15 row_mask:0xf bank_mask:0xf bound_ctrl:1
	v_fmac_f32_dpp v122, v38, v206 row_shl:15 row_mask:0xf bank_mask:0xf bound_ctrl:1
	v_fmac_f32_dpp v123, v39, v207 row_shl:15 row_mask:0xf bank_mask:0xf bound_ctrl:1
	v_pk_mul_f32 v[48:49], v[116:117], s[0:1]
	v_pk_mul_f32 v[50:51], v[118:119], s[0:1]
	v_pk_mul_f32 v[52:53], v[116:117], v[120:121]
	v_pk_mul_f32 v[54:55], v[118:119], v[122:123]
	v_exp_f32_e32 v48, v48
	v_exp_f32_e32 v49, v49
	v_exp_f32_e32 v50, v50
	v_exp_f32_e32 v51, v51
	v_cvt_pk_bf16_f32 v196, v40, v41
	v_cvt_pk_bf16_f32 v197, v42, v43
	v_cvt_pk_bf16_f32 v198, v32, v33
	v_cvt_pk_bf16_f32 v199, v34, v35
	v_pk_add_f32 v[48:49], v[48:49], 1.0 op_sel_hi:[1,0]
	v_pk_add_f32 v[50:51], v[50:51], 1.0 op_sel_hi:[1,0]
	v_rcp_f32_e32 v48, v48
	v_rcp_f32_e32 v49, v49
	v_rcp_f32_e32 v50, v50
	v_rcp_f32_e32 v51, v51
	s_nop 0
	v_pk_mul_f32 v[52:53], v[52:53], v[48:49]
	v_pk_mul_f32 v[54:55], v[54:55], v[50:51]
	v_cvt_pk_bf16_f32 v252, v52, v53
	v_cvt_pk_bf16_f32 v253, v54, v55
	s_and_saveexec_b64 vcc, s[8:9]
	global_store_dwordx2 v[244:245], v[252:253], off offset:8
	s_mov_b64 exec, vcc
	v_add_co_u32_e32 v250, vcc, 0xfffdf000, v250
	s_nop 1
	v_addc_co_u32_e32 v251, vcc, -1, v251, vcc
	v_add_co_u32_e32 v194, vcc, 0x1000, v250
	s_nop 1
	v_addc_co_u32_e32 v195, vcc, 0, v251, vcc
	s_and_saveexec_b64 vcc, s[14:15]
	global_store_dwordx2 v[250:251], v[196:197], off offset:8
	global_store_dwordx2 v[194:195], v[198:199], off offset:1544
	s_mov_b64 exec, vcc
	v_add_co_u32_e32 v244, vcc, 0xb0000, v246
	s_nop 1
	v_addc_co_u32_e32 v245, vcc, 0, v247, vcc
	v_add_co_u32_e32 v250, vcc, 0x16000, v248
	s_nop 1
	v_addc_co_u32_e32 v251, vcc, 0, v249, vcc
	v_add_co_u32_e32 v194, vcc, 0x1000, v250
	s_nop 1
	v_addc_co_u32_e32 v195, vcc, 0, v251, vcc
	v_mul_f32_e32 v116, v208, v28
	v_mul_f32_e32 v117, v209, v29
	v_mul_f32_e32 v118, v210, v30
	v_mul_f32_e32 v119, v211, v31
	v_mul_f32_e32 v120, v212, v20
	v_mul_f32_e32 v121, v213, v21
	v_mul_f32_e32 v122, v214, v22
	v_mul_f32_e32 v123, v215, v23
	v_fmac_f32_dpp v116, v28, v220 row_shr:1 row_mask:0xf bank_mask:0xf bound_ctrl:1
	v_fmac_f32_dpp v117, v29, v221 row_shr:1 row_mask:0xf bank_mask:0xf bound_ctrl:1
	v_fmac_f32_dpp v118, v30, v222 row_shr:1 row_mask:0xf bank_mask:0xf bound_ctrl:1
	v_fmac_f32_dpp v119, v31, v223 row_shr:1 row_mask:0xf bank_mask:0xf bound_ctrl:1
	v_fmac_f32_dpp v120, v20, v204 row_shr:1 row_mask:0xf bank_mask:0xf bound_ctrl:1
	v_fmac_f32_dpp v121, v21, v205 row_shr:1 row_mask:0xf bank_mask:0xf bound_ctrl:1
	v_fmac_f32_dpp v122, v22, v206 row_shr:1 row_mask:0xf bank_mask:0xf bound_ctrl:1
	v_fmac_f32_dpp v123, v23, v207 row_shr:1 row_mask:0xf bank_mask:0xf bound_ctrl:1
	v_fmac_f32_dpp v116, v28, v216 row_shl:1 row_mask:0xf bank_mask:0xf bound_ctrl:1
	v_fmac_f32_dpp v117, v29, v217 row_shl:1 row_mask:0xf bank_mask:0xf bound_ctrl:1
	v_fmac_f32_dpp v118, v30, v218 row_shl:1 row_mask:0xf bank_mask:0xf bound_ctrl:1
	v_fmac_f32_dpp v119, v31, v219 row_shl:1 row_mask:0xf bank_mask:0xf bound_ctrl:1
	v_fmac_f32_dpp v120, v20, v200 row_shl:1 row_mask:0xf bank_mask:0xf bound_ctrl:1
	v_fmac_f32_dpp v121, v21, v201 row_shl:1 row_mask:0xf bank_mask:0xf bound_ctrl:1
	v_fmac_f32_dpp v122, v22, v202 row_shl:1 row_mask:0xf bank_mask:0xf bound_ctrl:1
	v_fmac_f32_dpp v123, v23, v203 row_shl:1 row_mask:0xf bank_mask:0xf bound_ctrl:1
	v_fmac_f32_dpp v116, v24, v216 row_shr:15 row_mask:0xf bank_mask:0xf bound_ctrl:1
	v_fmac_f32_dpp v117, v25, v217 row_shr:15 row_mask:0xf bank_mask:0xf bound_ctrl:1
	v_fmac_f32_dpp v118, v26, v218 row_shr:15 row_mask:0xf bank_mask:0xf bound_ctrl:1
	v_fmac_f32_dpp v119, v27, v219 row_shr:15 row_mask:0xf bank_mask:0xf bound_ctrl:1
	v_fmac_f32_dpp v120, v16, v200 row_shr:15 row_mask:0xf bank_mask:0xf bound_ctrl:1
	v_fmac_f32_dpp v121, v17, v201 row_shr:15 row_mask:0xf bank_mask:0xf bound_ctrl:1
	v_fmac_f32_dpp v122, v18, v202 row_shr:15 row_mask:0xf bank_mask:0xf bound_ctrl:1
	v_fmac_f32_dpp v123, v19, v203 row_shr:15 row_mask:0xf bank_mask:0xf bound_ctrl:1
	v_pk_mul_f32 v[48:49], v[116:117], s[0:1]
	v_pk_mul_f32 v[50:51], v[118:119], s[0:1]
	v_pk_mul_f32 v[52:53], v[116:117], v[120:121]
	v_pk_mul_f32 v[54:55], v[118:119], v[122:123]
	v_exp_f32_e32 v48, v48
	v_exp_f32_e32 v49, v49
	v_exp_f32_e32 v50, v50
	v_exp_f32_e32 v51, v51
	v_cvt_pk_bf16_f32 v196, v28, v29
	v_cvt_pk_bf16_f32 v197, v30, v31
	v_cvt_pk_bf16_f32 v198, v20, v21
	v_cvt_pk_bf16_f32 v199, v22, v23
	v_pk_add_f32 v[48:49], v[48:49], 1.0 op_sel_hi:[1,0]
	v_pk_add_f32 v[50:51], v[50:51], 1.0 op_sel_hi:[1,0]
	v_rcp_f32_e32 v48, v48
	v_rcp_f32_e32 v49, v49
	v_rcp_f32_e32 v50, v50
	v_rcp_f32_e32 v51, v51
	s_nop 0
	v_pk_mul_f32 v[52:53], v[52:53], v[48:49]
	v_pk_mul_f32 v[54:55], v[54:55], v[50:51]
	v_cvt_pk_bf16_f32 v252, v52, v53
	v_cvt_pk_bf16_f32 v253, v54, v55
	s_and_saveexec_b64 vcc, s[10:11]
	global_store_dwordx2 v[244:245], v[252:253], off offset:8
	s_mov_b64 exec, vcc
	s_and_saveexec_b64 vcc, s[12:13]
	global_store_dwordx2 v[250:251], v[196:197], off offset:8
	global_store_dwordx2 v[194:195], v[198:199], off offset:1544
	s_mov_b64 exec, vcc
	v_lshl_add_u64 v[244:245], v[244:245], 0, s[2:3]
	v_mul_f32_e32 v116, v208, v24
	v_mul_f32_e32 v117, v209, v25
	v_mul_f32_e32 v118, v210, v26
	v_mul_f32_e32 v119, v211, v27
	v_mul_f32_e32 v120, v212, v16
	v_mul_f32_e32 v121, v213, v17
	v_mul_f32_e32 v122, v214, v18
	v_mul_f32_e32 v123, v215, v19
	v_fmac_f32_dpp v116, v24, v220 row_shr:1 row_mask:0xf bank_mask:0xf bound_ctrl:1
	v_fmac_f32_dpp v117, v25, v221 row_shr:1 row_mask:0xf bank_mask:0xf bound_ctrl:1
	v_fmac_f32_dpp v118, v26, v222 row_shr:1 row_mask:0xf bank_mask:0xf bound_ctrl:1
	v_fmac_f32_dpp v119, v27, v223 row_shr:1 row_mask:0xf bank_mask:0xf bound_ctrl:1
	v_fmac_f32_dpp v120, v16, v204 row_shr:1 row_mask:0xf bank_mask:0xf bound_ctrl:1
	v_fmac_f32_dpp v121, v17, v205 row_shr:1 row_mask:0xf bank_mask:0xf bound_ctrl:1
	v_fmac_f32_dpp v122, v18, v206 row_shr:1 row_mask:0xf bank_mask:0xf bound_ctrl:1
	v_fmac_f32_dpp v123, v19, v207 row_shr:1 row_mask:0xf bank_mask:0xf bound_ctrl:1
	v_fmac_f32_dpp v116, v24, v216 row_shl:1 row_mask:0xf bank_mask:0xf bound_ctrl:1
	v_fmac_f32_dpp v117, v25, v217 row_shl:1 row_mask:0xf bank_mask:0xf bound_ctrl:1
	v_fmac_f32_dpp v118, v26, v218 row_shl:1 row_mask:0xf bank_mask:0xf bound_ctrl:1
	v_fmac_f32_dpp v119, v27, v219 row_shl:1 row_mask:0xf bank_mask:0xf bound_ctrl:1
	v_fmac_f32_dpp v120, v16, v200 row_shl:1 row_mask:0xf bank_mask:0xf bound_ctrl:1
	v_fmac_f32_dpp v121, v17, v201 row_shl:1 row_mask:0xf bank_mask:0xf bound_ctrl:1
	v_fmac_f32_dpp v122, v18, v202 row_shl:1 row_mask:0xf bank_mask:0xf bound_ctrl:1
	v_fmac_f32_dpp v123, v19, v203 row_shl:1 row_mask:0xf bank_mask:0xf bound_ctrl:1
	v_fmac_f32_dpp v116, v28, v220 row_shl:15 row_mask:0xf bank_mask:0xf bound_ctrl:1
	v_fmac_f32_dpp v117, v29, v221 row_shl:15 row_mask:0xf bank_mask:0xf bound_ctrl:1
	v_fmac_f32_dpp v118, v30, v222 row_shl:15 row_mask:0xf bank_mask:0xf bound_ctrl:1
	v_fmac_f32_dpp v119, v31, v223 row_shl:15 row_mask:0xf bank_mask:0xf bound_ctrl:1
	v_fmac_f32_dpp v120, v20, v204 row_shl:15 row_mask:0xf bank_mask:0xf bound_ctrl:1
	v_fmac_f32_dpp v121, v21, v205 row_shl:15 row_mask:0xf bank_mask:0xf bound_ctrl:1
	v_fmac_f32_dpp v122, v22, v206 row_shl:15 row_mask:0xf bank_mask:0xf bound_ctrl:1
	v_fmac_f32_dpp v123, v23, v207 row_shl:15 row_mask:0xf bank_mask:0xf bound_ctrl:1
	v_fmac_f32_dpp v116, v12, v216 row_shr:15 row_mask:0xf bank_mask:0xf bound_ctrl:1
	v_fmac_f32_dpp v117, v13, v217 row_shr:15 row_mask:0xf bank_mask:0xf bound_ctrl:1
	v_fmac_f32_dpp v118, v14, v218 row_shr:15 row_mask:0xf bank_mask:0xf bound_ctrl:1
	v_fmac_f32_dpp v119, v15, v219 row_shr:15 row_mask:0xf bank_mask:0xf bound_ctrl:1
	v_fmac_f32_dpp v120, v4, v200 row_shr:15 row_mask:0xf bank_mask:0xf bound_ctrl:1
	v_fmac_f32_dpp v121, v5, v201 row_shr:15 row_mask:0xf bank_mask:0xf bound_ctrl:1
	v_fmac_f32_dpp v122, v6, v202 row_shr:15 row_mask:0xf bank_mask:0xf bound_ctrl:1
	v_fmac_f32_dpp v123, v7, v203 row_shr:15 row_mask:0xf bank_mask:0xf bound_ctrl:1
	v_pk_mul_f32 v[48:49], v[116:117], s[0:1]
	v_pk_mul_f32 v[50:51], v[118:119], s[0:1]
	v_pk_mul_f32 v[52:53], v[116:117], v[120:121]
	v_pk_mul_f32 v[54:55], v[118:119], v[122:123]
	v_exp_f32_e32 v48, v48
	v_exp_f32_e32 v49, v49
	v_exp_f32_e32 v50, v50
	v_exp_f32_e32 v51, v51
	s_nop 0
	v_pk_add_f32 v[48:49], v[48:49], 1.0 op_sel_hi:[1,0]
	v_pk_add_f32 v[50:51], v[50:51], 1.0 op_sel_hi:[1,0]
	v_rcp_f32_e32 v48, v48
	v_rcp_f32_e32 v49, v49
	v_rcp_f32_e32 v50, v50
	v_rcp_f32_e32 v51, v51
	s_nop 0
	v_pk_mul_f32 v[52:53], v[52:53], v[48:49]
	v_pk_mul_f32 v[54:55], v[54:55], v[50:51]
	v_cvt_pk_bf16_f32 v252, v52, v53
	v_cvt_pk_bf16_f32 v253, v54, v55
	global_store_dwordx2 v[244:245], v[252:253], off offset:8
	v_lshl_add_u64 v[244:245], v[244:245], 0, s[2:3]
	v_mul_f32_e32 v116, v208, v12
	v_mul_f32_e32 v117, v209, v13
	v_mul_f32_e32 v118, v210, v14
	v_mul_f32_e32 v119, v211, v15
	v_mul_f32_e32 v120, v212, v4
	v_mul_f32_e32 v121, v213, v5
	v_mul_f32_e32 v122, v214, v6
	v_mul_f32_e32 v123, v215, v7
	v_fmac_f32_dpp v116, v12, v220 row_shr:1 row_mask:0xf bank_mask:0xf bound_ctrl:1
	v_fmac_f32_dpp v117, v13, v221 row_shr:1 row_mask:0xf bank_mask:0xf bound_ctrl:1
	v_fmac_f32_dpp v118, v14, v222 row_shr:1 row_mask:0xf bank_mask:0xf bound_ctrl:1
	v_fmac_f32_dpp v119, v15, v223 row_shr:1 row_mask:0xf bank_mask:0xf bound_ctrl:1
	v_fmac_f32_dpp v120, v4, v204 row_shr:1 row_mask:0xf bank_mask:0xf bound_ctrl:1
	v_fmac_f32_dpp v121, v5, v205 row_shr:1 row_mask:0xf bank_mask:0xf bound_ctrl:1
	v_fmac_f32_dpp v122, v6, v206 row_shr:1 row_mask:0xf bank_mask:0xf bound_ctrl:1
	v_fmac_f32_dpp v123, v7, v207 row_shr:1 row_mask:0xf bank_mask:0xf bound_ctrl:1
	v_fmac_f32_dpp v116, v12, v216 row_shl:1 row_mask:0xf bank_mask:0xf bound_ctrl:1
	v_fmac_f32_dpp v117, v13, v217 row_shl:1 row_mask:0xf bank_mask:0xf bound_ctrl:1
	v_fmac_f32_dpp v118, v14, v218 row_shl:1 row_mask:0xf bank_mask:0xf bound_ctrl:1
	v_fmac_f32_dpp v119, v15, v219 row_shl:1 row_mask:0xf bank_mask:0xf bound_ctrl:1
	v_fmac_f32_dpp v120, v4, v200 row_shl:1 row_mask:0xf bank_mask:0xf bound_ctrl:1
	v_fmac_f32_dpp v121, v5, v201 row_shl:1 row_mask:0xf bank_mask:0xf bound_ctrl:1
	v_fmac_f32_dpp v122, v6, v202 row_shl:1 row_mask:0xf bank_mask:0xf bound_ctrl:1
	v_fmac_f32_dpp v123, v7, v203 row_shl:1 row_mask:0xf bank_mask:0xf bound_ctrl:1
	v_fmac_f32_dpp v116, v24, v220 row_shl:15 row_mask:0xf bank_mask:0xf bound_ctrl:1
	v_fmac_f32_dpp v117, v25, v221 row_shl:15 row_mask:0xf bank_mask:0xf bound_ctrl:1
	v_fmac_f32_dpp v118, v26, v222 row_shl:15 row_mask:0xf bank_mask:0xf bound_ctrl:1
	v_fmac_f32_dpp v119, v27, v223 row_shl:15 row_mask:0xf bank_mask:0xf bound_ctrl:1
	v_fmac_f32_dpp v120, v16, v204 row_shl:15 row_mask:0xf bank_mask:0xf bound_ctrl:1
	v_fmac_f32_dpp v121, v17, v205 row_shl:15 row_mask:0xf bank_mask:0xf bound_ctrl:1
	v_fmac_f32_dpp v122, v18, v206 row_shl:15 row_mask:0xf bank_mask:0xf bound_ctrl:1
	v_fmac_f32_dpp v123, v19, v207 row_shl:15 row_mask:0xf bank_mask:0xf bound_ctrl:1
	v_fmac_f32_dpp v116, v8, v216 row_shr:15 row_mask:0xf bank_mask:0xf bound_ctrl:1
	v_fmac_f32_dpp v117, v9, v217 row_shr:15 row_mask:0xf bank_mask:0xf bound_ctrl:1
	v_fmac_f32_dpp v118, v10, v218 row_shr:15 row_mask:0xf bank_mask:0xf bound_ctrl:1
	v_fmac_f32_dpp v119, v11, v219 row_shr:15 row_mask:0xf bank_mask:0xf bound_ctrl:1
	v_fmac_f32_dpp v120, v0, v200 row_shr:15 row_mask:0xf bank_mask:0xf bound_ctrl:1
	v_fmac_f32_dpp v121, v1, v201 row_shr:15 row_mask:0xf bank_mask:0xf bound_ctrl:1
	v_fmac_f32_dpp v122, v2, v202 row_shr:15 row_mask:0xf bank_mask:0xf bound_ctrl:1
	v_fmac_f32_dpp v123, v3, v203 row_shr:15 row_mask:0xf bank_mask:0xf bound_ctrl:1
	v_pk_mul_f32 v[48:49], v[116:117], s[0:1]
	v_pk_mul_f32 v[50:51], v[118:119], s[0:1]
	v_pk_mul_f32 v[52:53], v[116:117], v[120:121]
	v_pk_mul_f32 v[54:55], v[118:119], v[122:123]
	v_exp_f32_e32 v48, v48
	v_exp_f32_e32 v49, v49
	v_exp_f32_e32 v50, v50
	v_exp_f32_e32 v51, v51
	s_nop 0
	v_pk_add_f32 v[48:49], v[48:49], 1.0 op_sel_hi:[1,0]
	v_pk_add_f32 v[50:51], v[50:51], 1.0 op_sel_hi:[1,0]
	v_rcp_f32_e32 v48, v48
	v_rcp_f32_e32 v49, v49
	v_rcp_f32_e32 v50, v50
	v_rcp_f32_e32 v51, v51
	s_nop 0
	v_pk_mul_f32 v[52:53], v[52:53], v[48:49]
	v_pk_mul_f32 v[54:55], v[54:55], v[50:51]
	v_cvt_pk_bf16_f32 v252, v52, v53
	v_cvt_pk_bf16_f32 v253, v54, v55
	global_store_dwordx2 v[244:245], v[252:253], off offset:8
	v_lshl_add_u64 v[244:245], v[244:245], 0, s[2:3]
	v_mul_f32_e32 v116, v208, v8
	v_mul_f32_e32 v117, v209, v9
	v_mul_f32_e32 v118, v210, v10
	v_mul_f32_e32 v119, v211, v11
	v_mul_f32_e32 v120, v212, v0
	v_mul_f32_e32 v121, v213, v1
	v_mul_f32_e32 v122, v214, v2
	v_mul_f32_e32 v123, v215, v3
	v_fmac_f32_dpp v116, v8, v220 row_shr:1 row_mask:0xf bank_mask:0xf bound_ctrl:1
	v_fmac_f32_dpp v117, v9, v221 row_shr:1 row_mask:0xf bank_mask:0xf bound_ctrl:1
	v_fmac_f32_dpp v118, v10, v222 row_shr:1 row_mask:0xf bank_mask:0xf bound_ctrl:1
	v_fmac_f32_dpp v119, v11, v223 row_shr:1 row_mask:0xf bank_mask:0xf bound_ctrl:1
	v_fmac_f32_dpp v120, v0, v204 row_shr:1 row_mask:0xf bank_mask:0xf bound_ctrl:1
	v_fmac_f32_dpp v121, v1, v205 row_shr:1 row_mask:0xf bank_mask:0xf bound_ctrl:1
	v_fmac_f32_dpp v122, v2, v206 row_shr:1 row_mask:0xf bank_mask:0xf bound_ctrl:1
	v_fmac_f32_dpp v123, v3, v207 row_shr:1 row_mask:0xf bank_mask:0xf bound_ctrl:1
	v_fmac_f32_dpp v116, v8, v216 row_shl:1 row_mask:0xf bank_mask:0xf bound_ctrl:1
	v_fmac_f32_dpp v117, v9, v217 row_shl:1 row_mask:0xf bank_mask:0xf bound_ctrl:1
	v_fmac_f32_dpp v118, v10, v218 row_shl:1 row_mask:0xf bank_mask:0xf bound_ctrl:1
	v_fmac_f32_dpp v119, v11, v219 row_shl:1 row_mask:0xf bank_mask:0xf bound_ctrl:1
	v_fmac_f32_dpp v120, v0, v200 row_shl:1 row_mask:0xf bank_mask:0xf bound_ctrl:1
	v_fmac_f32_dpp v121, v1, v201 row_shl:1 row_mask:0xf bank_mask:0xf bound_ctrl:1
	v_fmac_f32_dpp v122, v2, v202 row_shl:1 row_mask:0xf bank_mask:0xf bound_ctrl:1
	v_fmac_f32_dpp v123, v3, v203 row_shl:1 row_mask:0xf bank_mask:0xf bound_ctrl:1
	v_fmac_f32_dpp v116, v12, v220 row_shl:15 row_mask:0xf bank_mask:0xf bound_ctrl:1
	v_fmac_f32_dpp v117, v13, v221 row_shl:15 row_mask:0xf bank_mask:0xf bound_ctrl:1
	v_fmac_f32_dpp v118, v14, v222 row_shl:15 row_mask:0xf bank_mask:0xf bound_ctrl:1
	v_fmac_f32_dpp v119, v15, v223 row_shl:15 row_mask:0xf bank_mask:0xf bound_ctrl:1
	v_fmac_f32_dpp v120, v4, v204 row_shl:15 row_mask:0xf bank_mask:0xf bound_ctrl:1
	v_fmac_f32_dpp v121, v5, v205 row_shl:15 row_mask:0xf bank_mask:0xf bound_ctrl:1
	v_fmac_f32_dpp v122, v6, v206 row_shl:15 row_mask:0xf bank_mask:0xf bound_ctrl:1
	v_fmac_f32_dpp v123, v7, v207 row_shl:15 row_mask:0xf bank_mask:0xf bound_ctrl:1
	v_pk_mul_f32 v[48:49], v[116:117], s[0:1]
	v_pk_mul_f32 v[50:51], v[118:119], s[0:1]
	v_pk_mul_f32 v[52:53], v[116:117], v[120:121]
	v_pk_mul_f32 v[54:55], v[118:119], v[122:123]
	v_exp_f32_e32 v48, v48
	v_exp_f32_e32 v49, v49
	v_exp_f32_e32 v50, v50
	v_exp_f32_e32 v51, v51
	v_cvt_pk_bf16_f32 v196, v8, v9
	v_cvt_pk_bf16_f32 v197, v10, v11
	v_cvt_pk_bf16_f32 v198, v0, v1
	v_cvt_pk_bf16_f32 v199, v2, v3
	v_pk_add_f32 v[48:49], v[48:49], 1.0 op_sel_hi:[1,0]
	v_pk_add_f32 v[50:51], v[50:51], 1.0 op_sel_hi:[1,0]
	v_rcp_f32_e32 v48, v48
	v_rcp_f32_e32 v49, v49
	v_rcp_f32_e32 v50, v50
	v_rcp_f32_e32 v51, v51
	s_nop 0
	v_pk_mul_f32 v[52:53], v[52:53], v[48:49]
	v_pk_mul_f32 v[54:55], v[54:55], v[50:51]
	v_cvt_pk_bf16_f32 v252, v52, v53
	v_cvt_pk_bf16_f32 v253, v54, v55
	s_and_saveexec_b64 vcc, s[8:9]
	global_store_dwordx2 v[244:245], v[252:253], off offset:8
	s_mov_b64 exec, vcc
	v_add_co_u32_e32 v250, vcc, 0xfffdf000, v250
	s_nop 1
	v_addc_co_u32_e32 v251, vcc, -1, v251, vcc
	v_add_co_u32_e32 v194, vcc, 0x1000, v250
	s_nop 1
	v_addc_co_u32_e32 v195, vcc, 0, v251, vcc
	s_and_saveexec_b64 vcc, s[14:15]
	global_store_dwordx2 v[250:251], v[196:197], off offset:8
	global_store_dwordx2 v[194:195], v[198:199], off offset:1544
	s_mov_b64 exec, vcc
	s_branch .LBB0_876
